# P0 transposes: tile decode cached per ring slot in SGPRs (store side no longer re-decodes), on the aligned version
# speedup vs baseline: 1.0020x; 1.0020x over previous
.LBB0_245:
	v_and_b32_e32 v64, 63, v182
	v_lshrrev_b32_e32 v65, 6, v182
	v_lshrrev_b32_e32 v66, 3, v182
	v_and_b32_e32 v67, 7, v182
	v_lshlrev_b32_e32 v67, 3, v67
	v_mul_u32_u24_e32 v68, 0x41, v65
	v_add_lshl_u32 v68, v68, v64, 2
	v_add_u32_e32 v68, 0x8000, v68
	v_mul_u32_u24_e32 v69, 0x41, v67
	v_add_lshl_u32 v69, v69, v66, 2
	v_add_u32_e32 v69, 0x8000, v69
	s_mov_b32 s22, 0x223e3c3a
	s_mov_b32 s23, 0x1e022624
	s_mov_b32 s4, s2
	s_mov_b32 s64, 0
	s_cmp_ge_u32 s4, 0x2c0
	s_addc_u32 s64, s64, 0
	s_cmp_ge_u32 s4, 0x580
	s_addc_u32 s64, s64, 0
	s_cmp_ge_u32 s4, 0x840
	s_addc_u32 s64, s64, 0
	s_cmp_ge_u32 s4, 0xb00
	s_addc_u32 s64, s64, 0
	s_cmp_ge_u32 s4, 0xdc0
	s_addc_u32 s64, s64, 0
	s_cmp_ge_u32 s4, 0x1080
	s_addc_u32 s64, s64, 0
	s_cmp_ge_u32 s4, 0x13c0
	s_addc_u32 s64, s64, 0
	s_mul_i32 s12, s64, 0x2c0
	s_cmp_eq_u32 s64, 7
	s_cselect_b32 s13, 0x80, 0
	s_add_i32 s12, s12, s13
	s_sub_i32 s6, s4, s12
	s_cmp_eq_u32 s64, 2
	s_cselect_b32 s14, 1, 0
	s_cmp_eq_u32 s64, 5
	s_cselect_b32 s14, 1, s14
	s_mul_i32 s12, s6, 0x5d2
	s_lshr_b32 s12, s12, 16
	s_mul_i32 s15, s12, 44
	s_sub_i32 s15, s6, s15
	s_lshr_b32 s13, s6, 4
	s_and_b32 s66, s6, 15
	s_cmp_eq_u32 s14, 1
	s_cselect_b32 s65, s12, s13
	s_cselect_b32 s66, s15, s66
	s_movk_i32 s68, 0x400
	s_cselect_b32 s68, 0xb00, s68
	s_movk_i32 s67, 0xb00
	s_cselect_b32 s67, 0x400, s67
	s_cmp_eq_u32 s64, 7
	s_cselect_b32 s67, 0x400, s67
	s_cmp_eq_u32 s64, 6
	s_cselect_b32 s67, 0xd00, s67
	s_lshl_b32 s12, s64, 3
	s_lshr_b64 s[12:13], s[22:23], s12
	s_and_b32 s12, s12, 0xff
	s_add_i32 s13, s12, 1
	v_readlane_b32 s16, v241, s12
	v_readlane_b32 s17, v241, s13
	v_mul_u32_u24_e32 v70, s67, v65
	s_mul_i32 s14, s66, s67
	s_add_i32 s14, s14, s65
	s_lshl_b32 s14, s14, 8
	v_add_lshl_u32 v70, v70, v64, 2
	s_add_u32 s18, s16, s14
	s_addc_u32 s19, s17, 0
	s_lshl_b32 s15, s67, 5
	global_load_dword v72, v70, s[18:19]
	s_add_u32 s18, s18, s15
	s_addc_u32 s19, s19, 0
	global_load_dword v73, v70, s[18:19]
	s_add_u32 s18, s18, s15
	s_addc_u32 s19, s19, 0
	global_load_dword v74, v70, s[18:19]
	s_add_u32 s18, s18, s15
	s_addc_u32 s19, s19, 0
	global_load_dword v75, v70, s[18:19]
	s_add_u32 s18, s18, s15
	s_addc_u32 s19, s19, 0
	global_load_dword v76, v70, s[18:19]
	s_add_u32 s18, s18, s15
	s_addc_u32 s19, s19, 0
	global_load_dword v77, v70, s[18:19]
	s_add_u32 s18, s18, s15
	s_addc_u32 s19, s19, 0
	global_load_dword v78, v70, s[18:19]
	s_add_u32 s18, s18, s15
	s_addc_u32 s19, s19, 0
	global_load_dword v79, v70, s[18:19]
	s_add_i32 s4, s2, 0x100
	s_mov_b32 s69, 0
	s_cmp_ge_u32 s4, 0x2c0
	s_addc_u32 s69, s69, 0
	s_cmp_ge_u32 s4, 0x580
	s_addc_u32 s69, s69, 0
	s_cmp_ge_u32 s4, 0x840
	s_addc_u32 s69, s69, 0
	s_cmp_ge_u32 s4, 0xb00
	s_addc_u32 s69, s69, 0
	s_cmp_ge_u32 s4, 0xdc0
	s_addc_u32 s69, s69, 0
	s_cmp_ge_u32 s4, 0x1080
	s_addc_u32 s69, s69, 0
	s_cmp_ge_u32 s4, 0x13c0
	s_addc_u32 s69, s69, 0
	s_mul_i32 s12, s69, 0x2c0
	s_cmp_eq_u32 s69, 7
	s_cselect_b32 s13, 0x80, 0
	s_add_i32 s12, s12, s13
	s_sub_i32 s6, s4, s12
	s_cmp_eq_u32 s69, 2
	s_cselect_b32 s14, 1, 0
	s_cmp_eq_u32 s69, 5
	s_cselect_b32 s14, 1, s14
	s_mul_i32 s12, s6, 0x5d2
	s_lshr_b32 s12, s12, 16
	s_mul_i32 s15, s12, 44
	s_sub_i32 s15, s6, s15
	s_lshr_b32 s13, s6, 4
	s_and_b32 s71, s6, 15
	s_cmp_eq_u32 s14, 1
	s_cselect_b32 s70, s12, s13
	s_cselect_b32 s71, s15, s71
	s_movk_i32 s73, 0x400
	s_cselect_b32 s73, 0xb00, s73
	s_movk_i32 s72, 0xb00
	s_cselect_b32 s72, 0x400, s72
	s_cmp_eq_u32 s69, 7
	s_cselect_b32 s72, 0x400, s72
	s_cmp_eq_u32 s69, 6
	s_cselect_b32 s72, 0xd00, s72
	s_lshl_b32 s12, s69, 3
	s_lshr_b64 s[12:13], s[22:23], s12
	s_and_b32 s12, s12, 0xff
	s_add_i32 s13, s12, 1
	v_readlane_b32 s16, v241, s12
	v_readlane_b32 s17, v241, s13
	v_mul_u32_u24_e32 v70, s72, v65
	s_mul_i32 s14, s71, s72
	s_add_i32 s14, s14, s70
	s_lshl_b32 s14, s14, 8
	v_add_lshl_u32 v70, v70, v64, 2
	s_add_u32 s18, s16, s14
	s_addc_u32 s19, s17, 0
	s_lshl_b32 s15, s72, 5
	global_load_dword v80, v70, s[18:19]
	s_add_u32 s18, s18, s15
	s_addc_u32 s19, s19, 0
	global_load_dword v81, v70, s[18:19]
	s_add_u32 s18, s18, s15
	s_addc_u32 s19, s19, 0
	global_load_dword v82, v70, s[18:19]
	s_add_u32 s18, s18, s15
	s_addc_u32 s19, s19, 0
	global_load_dword v83, v70, s[18:19]
	s_add_u32 s18, s18, s15
	s_addc_u32 s19, s19, 0
	global_load_dword v84, v70, s[18:19]
	s_add_u32 s18, s18, s15
	s_addc_u32 s19, s19, 0
	global_load_dword v85, v70, s[18:19]
	s_add_u32 s18, s18, s15
	s_addc_u32 s19, s19, 0
	global_load_dword v86, v70, s[18:19]
	s_add_u32 s18, s18, s15
	s_addc_u32 s19, s19, 0
	global_load_dword v87, v70, s[18:19]
	s_add_i32 s4, s2, 0x200
	s_mov_b32 s74, 0
	s_cmp_ge_u32 s4, 0x2c0
	s_addc_u32 s74, s74, 0
	s_cmp_ge_u32 s4, 0x580
	s_addc_u32 s74, s74, 0
	s_cmp_ge_u32 s4, 0x840
	s_addc_u32 s74, s74, 0
	s_cmp_ge_u32 s4, 0xb00
	s_addc_u32 s74, s74, 0
	s_cmp_ge_u32 s4, 0xdc0
	s_addc_u32 s74, s74, 0
	s_cmp_ge_u32 s4, 0x1080
	s_addc_u32 s74, s74, 0
	s_cmp_ge_u32 s4, 0x13c0
	s_addc_u32 s74, s74, 0
	s_mul_i32 s12, s74, 0x2c0
	s_cmp_eq_u32 s74, 7
	s_cselect_b32 s13, 0x80, 0
	s_add_i32 s12, s12, s13
	s_sub_i32 s6, s4, s12
	s_cmp_eq_u32 s74, 2
	s_cselect_b32 s14, 1, 0
	s_cmp_eq_u32 s74, 5
	s_cselect_b32 s14, 1, s14
	s_mul_i32 s12, s6, 0x5d2
	s_lshr_b32 s12, s12, 16
	s_mul_i32 s15, s12, 44
	s_sub_i32 s15, s6, s15
	s_lshr_b32 s13, s6, 4
	s_and_b32 s76, s6, 15
	s_cmp_eq_u32 s14, 1
	s_cselect_b32 s75, s12, s13
	s_cselect_b32 s76, s15, s76
	s_movk_i32 s78, 0x400
	s_cselect_b32 s78, 0xb00, s78
	s_movk_i32 s77, 0xb00
	s_cselect_b32 s77, 0x400, s77
	s_cmp_eq_u32 s74, 7
	s_cselect_b32 s77, 0x400, s77
	s_cmp_eq_u32 s74, 6
	s_cselect_b32 s77, 0xd00, s77
	s_lshl_b32 s12, s74, 3
	s_lshr_b64 s[12:13], s[22:23], s12
	s_and_b32 s12, s12, 0xff
	s_add_i32 s13, s12, 1
	v_readlane_b32 s16, v241, s12
	v_readlane_b32 s17, v241, s13
	v_mul_u32_u24_e32 v70, s77, v65
	s_mul_i32 s14, s76, s77
	s_add_i32 s14, s14, s75
	s_lshl_b32 s14, s14, 8
	v_add_lshl_u32 v70, v70, v64, 2
	s_add_u32 s18, s16, s14
	s_addc_u32 s19, s17, 0
	s_lshl_b32 s15, s77, 5
	global_load_dword v88, v70, s[18:19]
	s_add_u32 s18, s18, s15
	s_addc_u32 s19, s19, 0
	global_load_dword v89, v70, s[18:19]
	s_add_u32 s18, s18, s15
	s_addc_u32 s19, s19, 0
	global_load_dword v90, v70, s[18:19]
	s_add_u32 s18, s18, s15
	s_addc_u32 s19, s19, 0
	global_load_dword v91, v70, s[18:19]
	s_add_u32 s18, s18, s15
	s_addc_u32 s19, s19, 0
	global_load_dword v92, v70, s[18:19]
	s_add_u32 s18, s18, s15
	s_addc_u32 s19, s19, 0
	global_load_dword v93, v70, s[18:19]
	s_add_u32 s18, s18, s15
	s_addc_u32 s19, s19, 0
	global_load_dword v94, v70, s[18:19]
	s_add_u32 s18, s18, s15
	s_addc_u32 s19, s19, 0
	global_load_dword v95, v70, s[18:19]
	s_add_i32 s4, s2, 0x300
	s_mov_b32 s79, 0
	s_cmp_ge_u32 s4, 0x2c0
	s_addc_u32 s79, s79, 0
	s_cmp_ge_u32 s4, 0x580
	s_addc_u32 s79, s79, 0
	s_cmp_ge_u32 s4, 0x840
	s_addc_u32 s79, s79, 0
	s_cmp_ge_u32 s4, 0xb00
	s_addc_u32 s79, s79, 0
	s_cmp_ge_u32 s4, 0xdc0
	s_addc_u32 s79, s79, 0
	s_cmp_ge_u32 s4, 0x1080
	s_addc_u32 s79, s79, 0
	s_cmp_ge_u32 s4, 0x13c0
	s_addc_u32 s79, s79, 0
	s_mul_i32 s12, s79, 0x2c0
	s_cmp_eq_u32 s79, 7
	s_cselect_b32 s13, 0x80, 0
	s_add_i32 s12, s12, s13
	s_sub_i32 s6, s4, s12
	s_cmp_eq_u32 s79, 2
	s_cselect_b32 s14, 1, 0
	s_cmp_eq_u32 s79, 5
	s_cselect_b32 s14, 1, s14
	s_mul_i32 s12, s6, 0x5d2
	s_lshr_b32 s12, s12, 16
	s_mul_i32 s15, s12, 44
	s_sub_i32 s15, s6, s15
	s_lshr_b32 s13, s6, 4
	s_and_b32 s35, s6, 15
	s_cmp_eq_u32 s14, 1
	s_cselect_b32 s34, s12, s13
	s_cselect_b32 s35, s15, s35
	s_movk_i32 s37, 0x400
	s_cselect_b32 s37, 0xb00, s37
	s_movk_i32 s36, 0xb00
	s_cselect_b32 s36, 0x400, s36
	s_cmp_eq_u32 s79, 7
	s_cselect_b32 s36, 0x400, s36
	s_cmp_eq_u32 s79, 6
	s_cselect_b32 s36, 0xd00, s36
	s_lshl_b32 s12, s79, 3
	s_lshr_b64 s[12:13], s[22:23], s12
	s_and_b32 s12, s12, 0xff
	s_add_i32 s13, s12, 1
	v_readlane_b32 s16, v241, s12
	v_readlane_b32 s17, v241, s13
	v_mul_u32_u24_e32 v70, s36, v65
	s_mul_i32 s14, s35, s36
	s_add_i32 s14, s14, s34
	s_lshl_b32 s14, s14, 8
	v_add_lshl_u32 v70, v70, v64, 2
	s_add_u32 s18, s16, s14
	s_addc_u32 s19, s17, 0
	s_lshl_b32 s15, s36, 5
	global_load_dword v96, v70, s[18:19]
	s_add_u32 s18, s18, s15
	s_addc_u32 s19, s19, 0
	global_load_dword v97, v70, s[18:19]
	s_add_u32 s18, s18, s15
	s_addc_u32 s19, s19, 0
	global_load_dword v98, v70, s[18:19]
	s_add_u32 s18, s18, s15
	s_addc_u32 s19, s19, 0
	global_load_dword v99, v70, s[18:19]
	s_add_u32 s18, s18, s15
	s_addc_u32 s19, s19, 0
	global_load_dword v100, v70, s[18:19]
	s_add_u32 s18, s18, s15
	s_addc_u32 s19, s19, 0
	global_load_dword v101, v70, s[18:19]
	s_add_u32 s18, s18, s15
	s_addc_u32 s19, s19, 0
	global_load_dword v102, v70, s[18:19]
	s_add_u32 s18, s18, s15
	s_addc_u32 s19, s19, 0
	global_load_dword v103, v70, s[18:19]
	s_waitcnt vmcnt(24)
	ds_write_b32 v68, v72
	ds_write_b32 v68, v73 offset:2080
	ds_write_b32 v68, v74 offset:4160
	ds_write_b32 v68, v75 offset:6240
	ds_write_b32 v68, v76 offset:8320
	ds_write_b32 v68, v77 offset:10400
	ds_write_b32 v68, v78 offset:12480
	ds_write_b32 v68, v79 offset:14560
	s_waitcnt lgkmcnt(0)
	s_barrier
	s_lshl_b32 s12, s65, 6
	s_lshr_b32 s13, s65, 1
	s_lshl_b32 s13, s13, 8
	s_and_b32 s15, s65, 1
	s_lshl_b32 s15, s15, 6
	s_add_i32 s13, s13, s15
	s_and_b32 s15, s64, 1
	s_cmp_eq_u32 s64, 1
	s_cselect_b32 s15, 0x80, 0
	s_cmp_eq_u32 s64, 4
	s_cselect_b32 s15, 0x80, s15
	s_add_i32 s13, s13, s15
	s_cmp_eq_u32 s67, 0xb00
	s_cselect_b32 s12, s13, s12
	s_mov_b32 s14, 0x30000
	s_cmp_eq_u32 s64, 1
	s_cselect_b32 s14, 0x30000, s14
	s_cmp_eq_u32 s64, 2
	s_cselect_b32 s14, 0xb30000, s14
	s_cmp_eq_u32 s64, 3
	s_cselect_b32 s14, 0x10b0000, s14
	s_cmp_eq_u32 s64, 4
	s_cselect_b32 s14, 0x10b0000, s14
	s_cmp_eq_u32 s64, 5
	s_cselect_b32 s14, 0x1bb0000, s14
	s_cmp_eq_u32 s64, 6
	s_cselect_b32 s14, 0x2130000, s14
	s_cmp_eq_u32 s64, 7
	s_cselect_b32 s14, 0x28f0000, s14
	s_cmp_eq_u32 s64, 6
	s_cselect_b32 s15, 1, 0
	s_cmp_ge_u32 s65, 24
	s_cselect_b32 s13, s15, 0
	s_cmp_eq_u32 s13, 1
	s_cselect_b32 s14, 0x2430000, s14
	s_cselect_b32 s13, 0x600, 0
	s_sub_i32 s12, s12, s13
	s_mul_i32 s12, s12, s68
	s_lshl_b32 s13, s66, 6
	s_add_i32 s12, s12, s13
	s_lshl_b32 s12, s12, 1
	s_add_u32 s12, s12, s14
	s_add_u32 s20, s30, s12
	s_addc_u32 s21, s31, 0
	v_mul_u32_u24_e32 v71, s68, v66
	v_add_lshl_u32 v71, v71, v67, 1
	ds_read_b32 v104, v69
	ds_read_b32 v105, v69 offset:260
	ds_read_b32 v106, v69 offset:520
	ds_read_b32 v107, v69 offset:780
	ds_read_b32 v108, v69 offset:1040
	ds_read_b32 v109, v69 offset:1300
	ds_read_b32 v110, v69 offset:1560
	ds_read_b32 v111, v69 offset:1820
	s_waitcnt lgkmcnt(0)
	v_cvt_pk_bf16_f32 v112, v104, v105
	v_cvt_pk_bf16_f32 v113, v106, v107
	v_cvt_pk_bf16_f32 v114, v108, v109
	v_cvt_pk_bf16_f32 v115, v110, v111
	global_store_dwordx4 v71, v[112:115], s[20:21]
	s_barrier
	s_add_i32 s4, s2, 0x400
	s_mov_b32 s64, 0
	s_cmp_ge_u32 s4, 0x2c0
	s_addc_u32 s64, s64, 0
	s_cmp_ge_u32 s4, 0x580
	s_addc_u32 s64, s64, 0
	s_cmp_ge_u32 s4, 0x840
	s_addc_u32 s64, s64, 0
	s_cmp_ge_u32 s4, 0xb00
	s_addc_u32 s64, s64, 0
	s_cmp_ge_u32 s4, 0xdc0
	s_addc_u32 s64, s64, 0
	s_cmp_ge_u32 s4, 0x1080
	s_addc_u32 s64, s64, 0
	s_cmp_ge_u32 s4, 0x13c0
	s_addc_u32 s64, s64, 0
	s_mul_i32 s12, s64, 0x2c0
	s_cmp_eq_u32 s64, 7
	s_cselect_b32 s13, 0x80, 0
	s_add_i32 s12, s12, s13
	s_sub_i32 s6, s4, s12
	s_cmp_eq_u32 s64, 2
	s_cselect_b32 s14, 1, 0
	s_cmp_eq_u32 s64, 5
	s_cselect_b32 s14, 1, s14
	s_mul_i32 s12, s6, 0x5d2
	s_lshr_b32 s12, s12, 16
	s_mul_i32 s15, s12, 44
	s_sub_i32 s15, s6, s15
	s_lshr_b32 s13, s6, 4
	s_and_b32 s66, s6, 15
	s_cmp_eq_u32 s14, 1
	s_cselect_b32 s65, s12, s13
	s_cselect_b32 s66, s15, s66
	s_movk_i32 s68, 0x400
	s_cselect_b32 s68, 0xb00, s68
	s_movk_i32 s67, 0xb00
	s_cselect_b32 s67, 0x400, s67
	s_cmp_eq_u32 s64, 7
	s_cselect_b32 s67, 0x400, s67
	s_cmp_eq_u32 s64, 6
	s_cselect_b32 s67, 0xd00, s67
	s_lshl_b32 s12, s64, 3
	s_lshr_b64 s[12:13], s[22:23], s12
	s_and_b32 s12, s12, 0xff
	s_add_i32 s13, s12, 1
	v_readlane_b32 s16, v241, s12
	v_readlane_b32 s17, v241, s13
	v_mul_u32_u24_e32 v70, s67, v65
	s_mul_i32 s14, s66, s67
	s_add_i32 s14, s14, s65
	s_lshl_b32 s14, s14, 8
	v_add_lshl_u32 v70, v70, v64, 2
	s_add_u32 s18, s16, s14
	s_addc_u32 s19, s17, 0
	s_lshl_b32 s15, s67, 5
	global_load_dword v72, v70, s[18:19]
	s_add_u32 s18, s18, s15
	s_addc_u32 s19, s19, 0
	global_load_dword v73, v70, s[18:19]
	s_add_u32 s18, s18, s15
	s_addc_u32 s19, s19, 0
	global_load_dword v74, v70, s[18:19]
	s_add_u32 s18, s18, s15
	s_addc_u32 s19, s19, 0
	global_load_dword v75, v70, s[18:19]
	s_add_u32 s18, s18, s15
	s_addc_u32 s19, s19, 0
	global_load_dword v76, v70, s[18:19]
	s_add_u32 s18, s18, s15
	s_addc_u32 s19, s19, 0
	global_load_dword v77, v70, s[18:19]
	s_add_u32 s18, s18, s15
	s_addc_u32 s19, s19, 0
	global_load_dword v78, v70, s[18:19]
	s_add_u32 s18, s18, s15
	s_addc_u32 s19, s19, 0
	global_load_dword v79, v70, s[18:19]
	s_waitcnt vmcnt(25)
	ds_write_b32 v68, v80
	ds_write_b32 v68, v81 offset:2080
	ds_write_b32 v68, v82 offset:4160
	ds_write_b32 v68, v83 offset:6240
	ds_write_b32 v68, v84 offset:8320
	ds_write_b32 v68, v85 offset:10400
	ds_write_b32 v68, v86 offset:12480
	ds_write_b32 v68, v87 offset:14560
	s_waitcnt lgkmcnt(0)
	s_barrier
	s_lshl_b32 s12, s70, 6
	s_lshr_b32 s13, s70, 1
	s_lshl_b32 s13, s13, 8
	s_and_b32 s15, s70, 1
	s_lshl_b32 s15, s15, 6
	s_add_i32 s13, s13, s15
	s_and_b32 s15, s69, 1
	s_cmp_eq_u32 s69, 1
	s_cselect_b32 s15, 0x80, 0
	s_cmp_eq_u32 s69, 4
	s_cselect_b32 s15, 0x80, s15
	s_add_i32 s13, s13, s15
	s_cmp_eq_u32 s72, 0xb00
	s_cselect_b32 s12, s13, s12
	s_mov_b32 s14, 0x30000
	s_cmp_eq_u32 s69, 1
	s_cselect_b32 s14, 0x30000, s14
	s_cmp_eq_u32 s69, 2
	s_cselect_b32 s14, 0xb30000, s14
	s_cmp_eq_u32 s69, 3
	s_cselect_b32 s14, 0x10b0000, s14
	s_cmp_eq_u32 s69, 4
	s_cselect_b32 s14, 0x10b0000, s14
	s_cmp_eq_u32 s69, 5
	s_cselect_b32 s14, 0x1bb0000, s14
	s_cmp_eq_u32 s69, 6
	s_cselect_b32 s14, 0x2130000, s14
	s_cmp_eq_u32 s69, 7
	s_cselect_b32 s14, 0x28f0000, s14
	s_cmp_eq_u32 s69, 6
	s_cselect_b32 s15, 1, 0
	s_cmp_ge_u32 s70, 24
	s_cselect_b32 s13, s15, 0
	s_cmp_eq_u32 s13, 1
	s_cselect_b32 s14, 0x2430000, s14
	s_cselect_b32 s13, 0x600, 0
	s_sub_i32 s12, s12, s13
	s_mul_i32 s12, s12, s73
	s_lshl_b32 s13, s71, 6
	s_add_i32 s12, s12, s13
	s_lshl_b32 s12, s12, 1
	s_add_u32 s12, s12, s14
	s_add_u32 s20, s30, s12
	s_addc_u32 s21, s31, 0
	v_mul_u32_u24_e32 v71, s73, v66
	v_add_lshl_u32 v71, v71, v67, 1
	ds_read_b32 v104, v69
	ds_read_b32 v105, v69 offset:260
	ds_read_b32 v106, v69 offset:520
	ds_read_b32 v107, v69 offset:780
	ds_read_b32 v108, v69 offset:1040
	ds_read_b32 v109, v69 offset:1300
	ds_read_b32 v110, v69 offset:1560
	ds_read_b32 v111, v69 offset:1820
	s_waitcnt lgkmcnt(0)
	v_cvt_pk_bf16_f32 v116, v104, v105
	v_cvt_pk_bf16_f32 v117, v106, v107
	v_cvt_pk_bf16_f32 v118, v108, v109
	v_cvt_pk_bf16_f32 v119, v110, v111
	global_store_dwordx4 v71, v[116:119], s[20:21]
	s_barrier
	s_add_i32 s4, s2, 0x500
	s_mov_b32 s69, 0
	s_cmp_ge_u32 s4, 0x2c0
	s_addc_u32 s69, s69, 0
	s_cmp_ge_u32 s4, 0x580
	s_addc_u32 s69, s69, 0
	s_cmp_ge_u32 s4, 0x840
	s_addc_u32 s69, s69, 0
	s_cmp_ge_u32 s4, 0xb00
	s_addc_u32 s69, s69, 0
	s_cmp_ge_u32 s4, 0xdc0
	s_addc_u32 s69, s69, 0
	s_cmp_ge_u32 s4, 0x1080
	s_addc_u32 s69, s69, 0
	s_cmp_ge_u32 s4, 0x13c0
	s_addc_u32 s69, s69, 0
	s_mul_i32 s12, s69, 0x2c0
	s_cmp_eq_u32 s69, 7
	s_cselect_b32 s13, 0x80, 0
	s_add_i32 s12, s12, s13
	s_sub_i32 s6, s4, s12
	s_cmp_eq_u32 s69, 2
	s_cselect_b32 s14, 1, 0
	s_cmp_eq_u32 s69, 5
	s_cselect_b32 s14, 1, s14
	s_mul_i32 s12, s6, 0x5d2
	s_lshr_b32 s12, s12, 16
	s_mul_i32 s15, s12, 44
	s_sub_i32 s15, s6, s15
	s_lshr_b32 s13, s6, 4
	s_and_b32 s71, s6, 15
	s_cmp_eq_u32 s14, 1
	s_cselect_b32 s70, s12, s13
	s_cselect_b32 s71, s15, s71
	s_movk_i32 s73, 0x400
	s_cselect_b32 s73, 0xb00, s73
	s_movk_i32 s72, 0xb00
	s_cselect_b32 s72, 0x400, s72
	s_cmp_eq_u32 s69, 7
	s_cselect_b32 s72, 0x400, s72
	s_cmp_eq_u32 s69, 6
	s_cselect_b32 s72, 0xd00, s72
	s_lshl_b32 s12, s69, 3
	s_lshr_b64 s[12:13], s[22:23], s12
	s_and_b32 s12, s12, 0xff
	s_add_i32 s13, s12, 1
	v_readlane_b32 s16, v241, s12
	v_readlane_b32 s17, v241, s13
	v_mul_u32_u24_e32 v70, s72, v65
	s_mul_i32 s14, s71, s72
	s_add_i32 s14, s14, s70
	s_lshl_b32 s14, s14, 8
	v_add_lshl_u32 v70, v70, v64, 2
	s_add_u32 s18, s16, s14
	s_addc_u32 s19, s17, 0
	s_lshl_b32 s15, s72, 5
	global_load_dword v80, v70, s[18:19]
	s_add_u32 s18, s18, s15
	s_addc_u32 s19, s19, 0
	global_load_dword v81, v70, s[18:19]
	s_add_u32 s18, s18, s15
	s_addc_u32 s19, s19, 0
	global_load_dword v82, v70, s[18:19]
	s_add_u32 s18, s18, s15
	s_addc_u32 s19, s19, 0
	global_load_dword v83, v70, s[18:19]
	s_add_u32 s18, s18, s15
	s_addc_u32 s19, s19, 0
	global_load_dword v84, v70, s[18:19]
	s_add_u32 s18, s18, s15
	s_addc_u32 s19, s19, 0
	global_load_dword v85, v70, s[18:19]
	s_add_u32 s18, s18, s15
	s_addc_u32 s19, s19, 0
	global_load_dword v86, v70, s[18:19]
	s_add_u32 s18, s18, s15
	s_addc_u32 s19, s19, 0
	global_load_dword v87, v70, s[18:19]
	s_waitcnt vmcnt(26)
	ds_write_b32 v68, v88
	ds_write_b32 v68, v89 offset:2080
	ds_write_b32 v68, v90 offset:4160
	ds_write_b32 v68, v91 offset:6240
	ds_write_b32 v68, v92 offset:8320
	ds_write_b32 v68, v93 offset:10400
	ds_write_b32 v68, v94 offset:12480
	ds_write_b32 v68, v95 offset:14560
	s_waitcnt lgkmcnt(0)
	s_barrier
	s_lshl_b32 s12, s75, 6
	s_lshr_b32 s13, s75, 1
	s_lshl_b32 s13, s13, 8
	s_and_b32 s15, s75, 1
	s_lshl_b32 s15, s15, 6
	s_add_i32 s13, s13, s15
	s_and_b32 s15, s74, 1
	s_cmp_eq_u32 s74, 1
	s_cselect_b32 s15, 0x80, 0
	s_cmp_eq_u32 s74, 4
	s_cselect_b32 s15, 0x80, s15
	s_add_i32 s13, s13, s15
	s_cmp_eq_u32 s77, 0xb00
	s_cselect_b32 s12, s13, s12
	s_mov_b32 s14, 0x30000
	s_cmp_eq_u32 s74, 1
	s_cselect_b32 s14, 0x30000, s14
	s_cmp_eq_u32 s74, 2
	s_cselect_b32 s14, 0xb30000, s14
	s_cmp_eq_u32 s74, 3
	s_cselect_b32 s14, 0x10b0000, s14
	s_cmp_eq_u32 s74, 4
	s_cselect_b32 s14, 0x10b0000, s14
	s_cmp_eq_u32 s74, 5
	s_cselect_b32 s14, 0x1bb0000, s14
	s_cmp_eq_u32 s74, 6
	s_cselect_b32 s14, 0x2130000, s14
	s_cmp_eq_u32 s74, 7
	s_cselect_b32 s14, 0x28f0000, s14
	s_cmp_eq_u32 s74, 6
	s_cselect_b32 s15, 1, 0
	s_cmp_ge_u32 s75, 24
	s_cselect_b32 s13, s15, 0
	s_cmp_eq_u32 s13, 1
	s_cselect_b32 s14, 0x2430000, s14
	s_cselect_b32 s13, 0x600, 0
	s_sub_i32 s12, s12, s13
	s_mul_i32 s12, s12, s78
	s_lshl_b32 s13, s76, 6
	s_add_i32 s12, s12, s13
	s_lshl_b32 s12, s12, 1
	s_add_u32 s12, s12, s14
	s_add_u32 s20, s30, s12
	s_addc_u32 s21, s31, 0
	v_mul_u32_u24_e32 v71, s78, v66
	v_add_lshl_u32 v71, v71, v67, 1
	ds_read_b32 v104, v69
	ds_read_b32 v105, v69 offset:260
	ds_read_b32 v106, v69 offset:520
	ds_read_b32 v107, v69 offset:780
	ds_read_b32 v108, v69 offset:1040
	ds_read_b32 v109, v69 offset:1300
	ds_read_b32 v110, v69 offset:1560
	ds_read_b32 v111, v69 offset:1820
	s_waitcnt lgkmcnt(0)
	v_cvt_pk_bf16_f32 v112, v104, v105
	v_cvt_pk_bf16_f32 v113, v106, v107
	v_cvt_pk_bf16_f32 v114, v108, v109
	v_cvt_pk_bf16_f32 v115, v110, v111
	global_store_dwordx4 v71, v[112:115], s[20:21]
	s_barrier
	s_add_i32 s4, s2, 0x600
	s_mov_b32 s74, 0
	s_cmp_ge_u32 s4, 0x2c0
	s_addc_u32 s74, s74, 0
	s_cmp_ge_u32 s4, 0x580
	s_addc_u32 s74, s74, 0
	s_cmp_ge_u32 s4, 0x840
	s_addc_u32 s74, s74, 0
	s_cmp_ge_u32 s4, 0xb00
	s_addc_u32 s74, s74, 0
	s_cmp_ge_u32 s4, 0xdc0
	s_addc_u32 s74, s74, 0
	s_cmp_ge_u32 s4, 0x1080
	s_addc_u32 s74, s74, 0
	s_cmp_ge_u32 s4, 0x13c0
	s_addc_u32 s74, s74, 0
	s_mul_i32 s12, s74, 0x2c0
	s_cmp_eq_u32 s74, 7
	s_cselect_b32 s13, 0x80, 0
	s_add_i32 s12, s12, s13
	s_sub_i32 s6, s4, s12
	s_cmp_eq_u32 s74, 2
	s_cselect_b32 s14, 1, 0
	s_cmp_eq_u32 s74, 5
	s_cselect_b32 s14, 1, s14
	s_mul_i32 s12, s6, 0x5d2
	s_lshr_b32 s12, s12, 16
	s_mul_i32 s15, s12, 44
	s_sub_i32 s15, s6, s15
	s_lshr_b32 s13, s6, 4
	s_and_b32 s76, s6, 15
	s_cmp_eq_u32 s14, 1
	s_cselect_b32 s75, s12, s13
	s_cselect_b32 s76, s15, s76
	s_movk_i32 s78, 0x400
	s_cselect_b32 s78, 0xb00, s78
	s_movk_i32 s77, 0xb00
	s_cselect_b32 s77, 0x400, s77
	s_cmp_eq_u32 s74, 7
	s_cselect_b32 s77, 0x400, s77
	s_cmp_eq_u32 s74, 6
	s_cselect_b32 s77, 0xd00, s77
	s_lshl_b32 s12, s74, 3
	s_lshr_b64 s[12:13], s[22:23], s12
	s_and_b32 s12, s12, 0xff
	s_add_i32 s13, s12, 1
	v_readlane_b32 s16, v241, s12
	v_readlane_b32 s17, v241, s13
	v_mul_u32_u24_e32 v70, s77, v65
	s_mul_i32 s14, s76, s77
	s_add_i32 s14, s14, s75
	s_lshl_b32 s14, s14, 8
	v_add_lshl_u32 v70, v70, v64, 2
	s_add_u32 s18, s16, s14
	s_addc_u32 s19, s17, 0
	s_lshl_b32 s15, s77, 5
	global_load_dword v88, v70, s[18:19]
	s_add_u32 s18, s18, s15
	s_addc_u32 s19, s19, 0
	global_load_dword v89, v70, s[18:19]
	s_add_u32 s18, s18, s15
	s_addc_u32 s19, s19, 0
	global_load_dword v90, v70, s[18:19]
	s_add_u32 s18, s18, s15
	s_addc_u32 s19, s19, 0
	global_load_dword v91, v70, s[18:19]
	s_add_u32 s18, s18, s15
	s_addc_u32 s19, s19, 0
	global_load_dword v92, v70, s[18:19]
	s_add_u32 s18, s18, s15
	s_addc_u32 s19, s19, 0
	global_load_dword v93, v70, s[18:19]
	s_add_u32 s18, s18, s15
	s_addc_u32 s19, s19, 0
	global_load_dword v94, v70, s[18:19]
	s_add_u32 s18, s18, s15
	s_addc_u32 s19, s19, 0
	global_load_dword v95, v70, s[18:19]
	s_waitcnt vmcnt(27)
	ds_write_b32 v68, v96
	ds_write_b32 v68, v97 offset:2080
	ds_write_b32 v68, v98 offset:4160
	ds_write_b32 v68, v99 offset:6240
	ds_write_b32 v68, v100 offset:8320
	ds_write_b32 v68, v101 offset:10400
	ds_write_b32 v68, v102 offset:12480
	ds_write_b32 v68, v103 offset:14560
	s_waitcnt lgkmcnt(0)
	s_barrier
	s_lshl_b32 s12, s34, 6
	s_lshr_b32 s13, s34, 1
	s_lshl_b32 s13, s13, 8
	s_and_b32 s15, s34, 1
	s_lshl_b32 s15, s15, 6
	s_add_i32 s13, s13, s15
	s_and_b32 s15, s79, 1
	s_cmp_eq_u32 s79, 1
	s_cselect_b32 s15, 0x80, 0
	s_cmp_eq_u32 s79, 4
	s_cselect_b32 s15, 0x80, s15
	s_add_i32 s13, s13, s15
	s_cmp_eq_u32 s36, 0xb00
	s_cselect_b32 s12, s13, s12
	s_mov_b32 s14, 0x30000
	s_cmp_eq_u32 s79, 1
	s_cselect_b32 s14, 0x30000, s14
	s_cmp_eq_u32 s79, 2
	s_cselect_b32 s14, 0xb30000, s14
	s_cmp_eq_u32 s79, 3
	s_cselect_b32 s14, 0x10b0000, s14
	s_cmp_eq_u32 s79, 4
	s_cselect_b32 s14, 0x10b0000, s14
	s_cmp_eq_u32 s79, 5
	s_cselect_b32 s14, 0x1bb0000, s14
	s_cmp_eq_u32 s79, 6
	s_cselect_b32 s14, 0x2130000, s14
	s_cmp_eq_u32 s79, 7
	s_cselect_b32 s14, 0x28f0000, s14
	s_cmp_eq_u32 s79, 6
	s_cselect_b32 s15, 1, 0
	s_cmp_ge_u32 s34, 24
	s_cselect_b32 s13, s15, 0
	s_cmp_eq_u32 s13, 1
	s_cselect_b32 s14, 0x2430000, s14
	s_cselect_b32 s13, 0x600, 0
	s_sub_i32 s12, s12, s13
	s_mul_i32 s12, s12, s37
	s_lshl_b32 s13, s35, 6
	s_add_i32 s12, s12, s13
	s_lshl_b32 s12, s12, 1
	s_add_u32 s12, s12, s14
	s_add_u32 s20, s30, s12
	s_addc_u32 s21, s31, 0
	v_mul_u32_u24_e32 v71, s37, v66
	v_add_lshl_u32 v71, v71, v67, 1
	ds_read_b32 v104, v69
	ds_read_b32 v105, v69 offset:260
	ds_read_b32 v106, v69 offset:520
	ds_read_b32 v107, v69 offset:780
	ds_read_b32 v108, v69 offset:1040
	ds_read_b32 v109, v69 offset:1300
	ds_read_b32 v110, v69 offset:1560
	ds_read_b32 v111, v69 offset:1820
	s_waitcnt lgkmcnt(0)
	v_cvt_pk_bf16_f32 v116, v104, v105
	v_cvt_pk_bf16_f32 v117, v106, v107
	v_cvt_pk_bf16_f32 v118, v108, v109
	v_cvt_pk_bf16_f32 v119, v110, v111
	global_store_dwordx4 v71, v[116:119], s[20:21]
	s_barrier
	s_add_i32 s4, s2, 0x700
	s_mov_b32 s79, 0
	s_cmp_ge_u32 s4, 0x2c0
	s_addc_u32 s79, s79, 0
	s_cmp_ge_u32 s4, 0x580
	s_addc_u32 s79, s79, 0
	s_cmp_ge_u32 s4, 0x840
	s_addc_u32 s79, s79, 0
	s_cmp_ge_u32 s4, 0xb00
	s_addc_u32 s79, s79, 0
	s_cmp_ge_u32 s4, 0xdc0
	s_addc_u32 s79, s79, 0
	s_cmp_ge_u32 s4, 0x1080
	s_addc_u32 s79, s79, 0
	s_cmp_ge_u32 s4, 0x13c0
	s_addc_u32 s79, s79, 0
	s_mul_i32 s12, s79, 0x2c0
	s_cmp_eq_u32 s79, 7
	s_cselect_b32 s13, 0x80, 0
	s_add_i32 s12, s12, s13
	s_sub_i32 s6, s4, s12
	s_cmp_eq_u32 s79, 2
	s_cselect_b32 s14, 1, 0
	s_cmp_eq_u32 s79, 5
	s_cselect_b32 s14, 1, s14
	s_mul_i32 s12, s6, 0x5d2
	s_lshr_b32 s12, s12, 16
	s_mul_i32 s15, s12, 44
	s_sub_i32 s15, s6, s15
	s_lshr_b32 s13, s6, 4
	s_and_b32 s35, s6, 15
	s_cmp_eq_u32 s14, 1
	s_cselect_b32 s34, s12, s13
	s_cselect_b32 s35, s15, s35
	s_movk_i32 s37, 0x400
	s_cselect_b32 s37, 0xb00, s37
	s_movk_i32 s36, 0xb00
	s_cselect_b32 s36, 0x400, s36
	s_cmp_eq_u32 s79, 7
	s_cselect_b32 s36, 0x400, s36
	s_cmp_eq_u32 s79, 6
	s_cselect_b32 s36, 0xd00, s36
	s_lshl_b32 s12, s79, 3
	s_lshr_b64 s[12:13], s[22:23], s12
	s_and_b32 s12, s12, 0xff
	s_add_i32 s13, s12, 1
	v_readlane_b32 s16, v241, s12
	v_readlane_b32 s17, v241, s13
	v_mul_u32_u24_e32 v70, s36, v65
	s_mul_i32 s14, s35, s36
	s_add_i32 s14, s14, s34
	s_lshl_b32 s14, s14, 8
	v_add_lshl_u32 v70, v70, v64, 2
	s_add_u32 s18, s16, s14
	s_addc_u32 s19, s17, 0
	s_lshl_b32 s15, s36, 5
	global_load_dword v96, v70, s[18:19]
	s_add_u32 s18, s18, s15
	s_addc_u32 s19, s19, 0
	global_load_dword v97, v70, s[18:19]
	s_add_u32 s18, s18, s15
	s_addc_u32 s19, s19, 0
	global_load_dword v98, v70, s[18:19]
	s_add_u32 s18, s18, s15
	s_addc_u32 s19, s19, 0
	global_load_dword v99, v70, s[18:19]
	s_add_u32 s18, s18, s15
	s_addc_u32 s19, s19, 0
	global_load_dword v100, v70, s[18:19]
	s_add_u32 s18, s18, s15
	s_addc_u32 s19, s19, 0
	global_load_dword v101, v70, s[18:19]
	s_add_u32 s18, s18, s15
	s_addc_u32 s19, s19, 0
	global_load_dword v102, v70, s[18:19]
	s_add_u32 s18, s18, s15
	s_addc_u32 s19, s19, 0
	global_load_dword v103, v70, s[18:19]
	s_waitcnt vmcnt(27)
	ds_write_b32 v68, v72
	ds_write_b32 v68, v73 offset:2080
	ds_write_b32 v68, v74 offset:4160
	ds_write_b32 v68, v75 offset:6240
	ds_write_b32 v68, v76 offset:8320
	ds_write_b32 v68, v77 offset:10400
	ds_write_b32 v68, v78 offset:12480
	ds_write_b32 v68, v79 offset:14560
	s_waitcnt lgkmcnt(0)
	s_barrier
	s_lshl_b32 s12, s65, 6
	s_lshr_b32 s13, s65, 1
	s_lshl_b32 s13, s13, 8
	s_and_b32 s15, s65, 1
	s_lshl_b32 s15, s15, 6
	s_add_i32 s13, s13, s15
	s_and_b32 s15, s64, 1
	s_cmp_eq_u32 s64, 1
	s_cselect_b32 s15, 0x80, 0
	s_cmp_eq_u32 s64, 4
	s_cselect_b32 s15, 0x80, s15
	s_add_i32 s13, s13, s15
	s_cmp_eq_u32 s67, 0xb00
	s_cselect_b32 s12, s13, s12
	s_mov_b32 s14, 0x30000
	s_cmp_eq_u32 s64, 1
	s_cselect_b32 s14, 0x30000, s14
	s_cmp_eq_u32 s64, 2
	s_cselect_b32 s14, 0xb30000, s14
	s_cmp_eq_u32 s64, 3
	s_cselect_b32 s14, 0x10b0000, s14
	s_cmp_eq_u32 s64, 4
	s_cselect_b32 s14, 0x10b0000, s14
	s_cmp_eq_u32 s64, 5
	s_cselect_b32 s14, 0x1bb0000, s14
	s_cmp_eq_u32 s64, 6
	s_cselect_b32 s14, 0x2130000, s14
	s_cmp_eq_u32 s64, 7
	s_cselect_b32 s14, 0x28f0000, s14
	s_cmp_eq_u32 s64, 6
	s_cselect_b32 s15, 1, 0
	s_cmp_ge_u32 s65, 24
	s_cselect_b32 s13, s15, 0
	s_cmp_eq_u32 s13, 1
	s_cselect_b32 s14, 0x2430000, s14
	s_cselect_b32 s13, 0x600, 0
	s_sub_i32 s12, s12, s13
	s_mul_i32 s12, s12, s68
	s_lshl_b32 s13, s66, 6
	s_add_i32 s12, s12, s13
	s_lshl_b32 s12, s12, 1
	s_add_u32 s12, s12, s14
	s_add_u32 s20, s30, s12
	s_addc_u32 s21, s31, 0
	v_mul_u32_u24_e32 v71, s68, v66
	v_add_lshl_u32 v71, v71, v67, 1
	ds_read_b32 v104, v69
	ds_read_b32 v105, v69 offset:260
	ds_read_b32 v106, v69 offset:520
	ds_read_b32 v107, v69 offset:780
	ds_read_b32 v108, v69 offset:1040
	ds_read_b32 v109, v69 offset:1300
	ds_read_b32 v110, v69 offset:1560
	ds_read_b32 v111, v69 offset:1820
	s_waitcnt lgkmcnt(0)
	v_cvt_pk_bf16_f32 v112, v104, v105
	v_cvt_pk_bf16_f32 v113, v106, v107
	v_cvt_pk_bf16_f32 v114, v108, v109
	v_cvt_pk_bf16_f32 v115, v110, v111
	global_store_dwordx4 v71, v[112:115], s[20:21]
	s_barrier
	s_add_i32 s4, s2, 0x800
	s_mov_b32 s64, 0
	s_cmp_ge_u32 s4, 0x2c0
	s_addc_u32 s64, s64, 0
	s_cmp_ge_u32 s4, 0x580
	s_addc_u32 s64, s64, 0
	s_cmp_ge_u32 s4, 0x840
	s_addc_u32 s64, s64, 0
	s_cmp_ge_u32 s4, 0xb00
	s_addc_u32 s64, s64, 0
	s_cmp_ge_u32 s4, 0xdc0
	s_addc_u32 s64, s64, 0
	s_cmp_ge_u32 s4, 0x1080
	s_addc_u32 s64, s64, 0
	s_cmp_ge_u32 s4, 0x13c0
	s_addc_u32 s64, s64, 0
	s_mul_i32 s12, s64, 0x2c0
	s_cmp_eq_u32 s64, 7
	s_cselect_b32 s13, 0x80, 0
	s_add_i32 s12, s12, s13
	s_sub_i32 s6, s4, s12
	s_cmp_eq_u32 s64, 2
	s_cselect_b32 s14, 1, 0
	s_cmp_eq_u32 s64, 5
	s_cselect_b32 s14, 1, s14
	s_mul_i32 s12, s6, 0x5d2
	s_lshr_b32 s12, s12, 16
	s_mul_i32 s15, s12, 44
	s_sub_i32 s15, s6, s15
	s_lshr_b32 s13, s6, 4
	s_and_b32 s66, s6, 15
	s_cmp_eq_u32 s14, 1
	s_cselect_b32 s65, s12, s13
	s_cselect_b32 s66, s15, s66
	s_movk_i32 s68, 0x400
	s_cselect_b32 s68, 0xb00, s68
	s_movk_i32 s67, 0xb00
	s_cselect_b32 s67, 0x400, s67
	s_cmp_eq_u32 s64, 7
	s_cselect_b32 s67, 0x400, s67
	s_cmp_eq_u32 s64, 6
	s_cselect_b32 s67, 0xd00, s67
	s_lshl_b32 s12, s64, 3
	s_lshr_b64 s[12:13], s[22:23], s12
	s_and_b32 s12, s12, 0xff
	s_add_i32 s13, s12, 1
	v_readlane_b32 s16, v241, s12
	v_readlane_b32 s17, v241, s13
	v_mul_u32_u24_e32 v70, s67, v65
	s_mul_i32 s14, s66, s67
	s_add_i32 s14, s14, s65
	s_lshl_b32 s14, s14, 8
	v_add_lshl_u32 v70, v70, v64, 2
	s_add_u32 s18, s16, s14
	s_addc_u32 s19, s17, 0
	s_lshl_b32 s15, s67, 5
	global_load_dword v72, v70, s[18:19]
	s_add_u32 s18, s18, s15
	s_addc_u32 s19, s19, 0
	global_load_dword v73, v70, s[18:19]
	s_add_u32 s18, s18, s15
	s_addc_u32 s19, s19, 0
	global_load_dword v74, v70, s[18:19]
	s_add_u32 s18, s18, s15
	s_addc_u32 s19, s19, 0
	global_load_dword v75, v70, s[18:19]
	s_add_u32 s18, s18, s15
	s_addc_u32 s19, s19, 0
	global_load_dword v76, v70, s[18:19]
	s_add_u32 s18, s18, s15
	s_addc_u32 s19, s19, 0
	global_load_dword v77, v70, s[18:19]
	s_add_u32 s18, s18, s15
	s_addc_u32 s19, s19, 0
	global_load_dword v78, v70, s[18:19]
	s_add_u32 s18, s18, s15
	s_addc_u32 s19, s19, 0
	global_load_dword v79, v70, s[18:19]
	s_waitcnt vmcnt(27)
	ds_write_b32 v68, v80
	ds_write_b32 v68, v81 offset:2080
	ds_write_b32 v68, v82 offset:4160
	ds_write_b32 v68, v83 offset:6240
	ds_write_b32 v68, v84 offset:8320
	ds_write_b32 v68, v85 offset:10400
	ds_write_b32 v68, v86 offset:12480
	ds_write_b32 v68, v87 offset:14560
	s_waitcnt lgkmcnt(0)
	s_barrier
	s_lshl_b32 s12, s70, 6
	s_lshr_b32 s13, s70, 1
	s_lshl_b32 s13, s13, 8
	s_and_b32 s15, s70, 1
	s_lshl_b32 s15, s15, 6
	s_add_i32 s13, s13, s15
	s_and_b32 s15, s69, 1
	s_cmp_eq_u32 s69, 1
	s_cselect_b32 s15, 0x80, 0
	s_cmp_eq_u32 s69, 4
	s_cselect_b32 s15, 0x80, s15
	s_add_i32 s13, s13, s15
	s_cmp_eq_u32 s72, 0xb00
	s_cselect_b32 s12, s13, s12
	s_mov_b32 s14, 0x30000
	s_cmp_eq_u32 s69, 1
	s_cselect_b32 s14, 0x30000, s14
	s_cmp_eq_u32 s69, 2
	s_cselect_b32 s14, 0xb30000, s14
	s_cmp_eq_u32 s69, 3
	s_cselect_b32 s14, 0x10b0000, s14
	s_cmp_eq_u32 s69, 4
	s_cselect_b32 s14, 0x10b0000, s14
	s_cmp_eq_u32 s69, 5
	s_cselect_b32 s14, 0x1bb0000, s14
	s_cmp_eq_u32 s69, 6
	s_cselect_b32 s14, 0x2130000, s14
	s_cmp_eq_u32 s69, 7
	s_cselect_b32 s14, 0x28f0000, s14
	s_cmp_eq_u32 s69, 6
	s_cselect_b32 s15, 1, 0
	s_cmp_ge_u32 s70, 24
	s_cselect_b32 s13, s15, 0
	s_cmp_eq_u32 s13, 1
	s_cselect_b32 s14, 0x2430000, s14
	s_cselect_b32 s13, 0x600, 0
	s_sub_i32 s12, s12, s13
	s_mul_i32 s12, s12, s73
	s_lshl_b32 s13, s71, 6
	s_add_i32 s12, s12, s13
	s_lshl_b32 s12, s12, 1
	s_add_u32 s12, s12, s14
	s_add_u32 s20, s30, s12
	s_addc_u32 s21, s31, 0
	v_mul_u32_u24_e32 v71, s73, v66
	v_add_lshl_u32 v71, v71, v67, 1
	ds_read_b32 v104, v69
	ds_read_b32 v105, v69 offset:260
	ds_read_b32 v106, v69 offset:520
	ds_read_b32 v107, v69 offset:780
	ds_read_b32 v108, v69 offset:1040
	ds_read_b32 v109, v69 offset:1300
	ds_read_b32 v110, v69 offset:1560
	ds_read_b32 v111, v69 offset:1820
	s_waitcnt lgkmcnt(0)
	v_cvt_pk_bf16_f32 v116, v104, v105
	v_cvt_pk_bf16_f32 v117, v106, v107
	v_cvt_pk_bf16_f32 v118, v108, v109
	v_cvt_pk_bf16_f32 v119, v110, v111
	global_store_dwordx4 v71, v[116:119], s[20:21]
	s_barrier
	s_add_i32 s4, s2, 0x900
	s_mov_b32 s69, 0
	s_cmp_ge_u32 s4, 0x2c0
	s_addc_u32 s69, s69, 0
	s_cmp_ge_u32 s4, 0x580
	s_addc_u32 s69, s69, 0
	s_cmp_ge_u32 s4, 0x840
	s_addc_u32 s69, s69, 0
	s_cmp_ge_u32 s4, 0xb00
	s_addc_u32 s69, s69, 0
	s_cmp_ge_u32 s4, 0xdc0
	s_addc_u32 s69, s69, 0
	s_cmp_ge_u32 s4, 0x1080
	s_addc_u32 s69, s69, 0
	s_cmp_ge_u32 s4, 0x13c0
	s_addc_u32 s69, s69, 0
	s_mul_i32 s12, s69, 0x2c0
	s_cmp_eq_u32 s69, 7
	s_cselect_b32 s13, 0x80, 0
	s_add_i32 s12, s12, s13
	s_sub_i32 s6, s4, s12
	s_cmp_eq_u32 s69, 2
	s_cselect_b32 s14, 1, 0
	s_cmp_eq_u32 s69, 5
	s_cselect_b32 s14, 1, s14
	s_mul_i32 s12, s6, 0x5d2
	s_lshr_b32 s12, s12, 16
	s_mul_i32 s15, s12, 44
	s_sub_i32 s15, s6, s15
	s_lshr_b32 s13, s6, 4
	s_and_b32 s71, s6, 15
	s_cmp_eq_u32 s14, 1
	s_cselect_b32 s70, s12, s13
	s_cselect_b32 s71, s15, s71
	s_movk_i32 s73, 0x400
	s_cselect_b32 s73, 0xb00, s73
	s_movk_i32 s72, 0xb00
	s_cselect_b32 s72, 0x400, s72
	s_cmp_eq_u32 s69, 7
	s_cselect_b32 s72, 0x400, s72
	s_cmp_eq_u32 s69, 6
	s_cselect_b32 s72, 0xd00, s72
	s_lshl_b32 s12, s69, 3
	s_lshr_b64 s[12:13], s[22:23], s12
	s_and_b32 s12, s12, 0xff
	s_add_i32 s13, s12, 1
	v_readlane_b32 s16, v241, s12
	v_readlane_b32 s17, v241, s13
	v_mul_u32_u24_e32 v70, s72, v65
	s_mul_i32 s14, s71, s72
	s_add_i32 s14, s14, s70
	s_lshl_b32 s14, s14, 8
	v_add_lshl_u32 v70, v70, v64, 2
	s_add_u32 s18, s16, s14
	s_addc_u32 s19, s17, 0
	s_lshl_b32 s15, s72, 5
	global_load_dword v80, v70, s[18:19]
	s_add_u32 s18, s18, s15
	s_addc_u32 s19, s19, 0
	global_load_dword v81, v70, s[18:19]
	s_add_u32 s18, s18, s15
	s_addc_u32 s19, s19, 0
	global_load_dword v82, v70, s[18:19]
	s_add_u32 s18, s18, s15
	s_addc_u32 s19, s19, 0
	global_load_dword v83, v70, s[18:19]
	s_add_u32 s18, s18, s15
	s_addc_u32 s19, s19, 0
	global_load_dword v84, v70, s[18:19]
	s_add_u32 s18, s18, s15
	s_addc_u32 s19, s19, 0
	global_load_dword v85, v70, s[18:19]
	s_add_u32 s18, s18, s15
	s_addc_u32 s19, s19, 0
	global_load_dword v86, v70, s[18:19]
	s_add_u32 s18, s18, s15
	s_addc_u32 s19, s19, 0
	global_load_dword v87, v70, s[18:19]
	s_waitcnt vmcnt(27)
	ds_write_b32 v68, v88
	ds_write_b32 v68, v89 offset:2080
	ds_write_b32 v68, v90 offset:4160
	ds_write_b32 v68, v91 offset:6240
	ds_write_b32 v68, v92 offset:8320
	ds_write_b32 v68, v93 offset:10400
	ds_write_b32 v68, v94 offset:12480
	ds_write_b32 v68, v95 offset:14560
	s_waitcnt lgkmcnt(0)
	s_barrier
	s_lshl_b32 s12, s75, 6
	s_lshr_b32 s13, s75, 1
	s_lshl_b32 s13, s13, 8
	s_and_b32 s15, s75, 1
	s_lshl_b32 s15, s15, 6
	s_add_i32 s13, s13, s15
	s_and_b32 s15, s74, 1
	s_cmp_eq_u32 s74, 1
	s_cselect_b32 s15, 0x80, 0
	s_cmp_eq_u32 s74, 4
	s_cselect_b32 s15, 0x80, s15
	s_add_i32 s13, s13, s15
	s_cmp_eq_u32 s77, 0xb00
	s_cselect_b32 s12, s13, s12
	s_mov_b32 s14, 0x30000
	s_cmp_eq_u32 s74, 1
	s_cselect_b32 s14, 0x30000, s14
	s_cmp_eq_u32 s74, 2
	s_cselect_b32 s14, 0xb30000, s14
	s_cmp_eq_u32 s74, 3
	s_cselect_b32 s14, 0x10b0000, s14
	s_cmp_eq_u32 s74, 4
	s_cselect_b32 s14, 0x10b0000, s14
	s_cmp_eq_u32 s74, 5
	s_cselect_b32 s14, 0x1bb0000, s14
	s_cmp_eq_u32 s74, 6
	s_cselect_b32 s14, 0x2130000, s14
	s_cmp_eq_u32 s74, 7
	s_cselect_b32 s14, 0x28f0000, s14
	s_cmp_eq_u32 s74, 6
	s_cselect_b32 s15, 1, 0
	s_cmp_ge_u32 s75, 24
	s_cselect_b32 s13, s15, 0
	s_cmp_eq_u32 s13, 1
	s_cselect_b32 s14, 0x2430000, s14
	s_cselect_b32 s13, 0x600, 0
	s_sub_i32 s12, s12, s13
	s_mul_i32 s12, s12, s78
	s_lshl_b32 s13, s76, 6
	s_add_i32 s12, s12, s13
	s_lshl_b32 s12, s12, 1
	s_add_u32 s12, s12, s14
	s_add_u32 s20, s30, s12
	s_addc_u32 s21, s31, 0
	v_mul_u32_u24_e32 v71, s78, v66
	v_add_lshl_u32 v71, v71, v67, 1
	ds_read_b32 v104, v69
	ds_read_b32 v105, v69 offset:260
	ds_read_b32 v106, v69 offset:520
	ds_read_b32 v107, v69 offset:780
	ds_read_b32 v108, v69 offset:1040
	ds_read_b32 v109, v69 offset:1300
	ds_read_b32 v110, v69 offset:1560
	ds_read_b32 v111, v69 offset:1820
	s_waitcnt lgkmcnt(0)
	v_cvt_pk_bf16_f32 v112, v104, v105
	v_cvt_pk_bf16_f32 v113, v106, v107
	v_cvt_pk_bf16_f32 v114, v108, v109
	v_cvt_pk_bf16_f32 v115, v110, v111
	global_store_dwordx4 v71, v[112:115], s[20:21]
	s_barrier
	s_add_i32 s4, s2, 0xa00
	s_mov_b32 s74, 0
	s_cmp_ge_u32 s4, 0x2c0
	s_addc_u32 s74, s74, 0
	s_cmp_ge_u32 s4, 0x580
	s_addc_u32 s74, s74, 0
	s_cmp_ge_u32 s4, 0x840
	s_addc_u32 s74, s74, 0
	s_cmp_ge_u32 s4, 0xb00
	s_addc_u32 s74, s74, 0
	s_cmp_ge_u32 s4, 0xdc0
	s_addc_u32 s74, s74, 0
	s_cmp_ge_u32 s4, 0x1080
	s_addc_u32 s74, s74, 0
	s_cmp_ge_u32 s4, 0x13c0
	s_addc_u32 s74, s74, 0
	s_mul_i32 s12, s74, 0x2c0
	s_cmp_eq_u32 s74, 7
	s_cselect_b32 s13, 0x80, 0
	s_add_i32 s12, s12, s13
	s_sub_i32 s6, s4, s12
	s_cmp_eq_u32 s74, 2
	s_cselect_b32 s14, 1, 0
	s_cmp_eq_u32 s74, 5
	s_cselect_b32 s14, 1, s14
	s_mul_i32 s12, s6, 0x5d2
	s_lshr_b32 s12, s12, 16
	s_mul_i32 s15, s12, 44
	s_sub_i32 s15, s6, s15
	s_lshr_b32 s13, s6, 4
	s_and_b32 s76, s6, 15
	s_cmp_eq_u32 s14, 1
	s_cselect_b32 s75, s12, s13
	s_cselect_b32 s76, s15, s76
	s_movk_i32 s78, 0x400
	s_cselect_b32 s78, 0xb00, s78
	s_movk_i32 s77, 0xb00
	s_cselect_b32 s77, 0x400, s77
	s_cmp_eq_u32 s74, 7
	s_cselect_b32 s77, 0x400, s77
	s_cmp_eq_u32 s74, 6
	s_cselect_b32 s77, 0xd00, s77
	s_lshl_b32 s12, s74, 3
	s_lshr_b64 s[12:13], s[22:23], s12
	s_and_b32 s12, s12, 0xff
	s_add_i32 s13, s12, 1
	v_readlane_b32 s16, v241, s12
	v_readlane_b32 s17, v241, s13
	v_mul_u32_u24_e32 v70, s77, v65
	s_mul_i32 s14, s76, s77
	s_add_i32 s14, s14, s75
	s_lshl_b32 s14, s14, 8
	v_add_lshl_u32 v70, v70, v64, 2
	s_add_u32 s18, s16, s14
	s_addc_u32 s19, s17, 0
	s_lshl_b32 s15, s77, 5
	global_load_dword v88, v70, s[18:19]
	s_add_u32 s18, s18, s15
	s_addc_u32 s19, s19, 0
	global_load_dword v89, v70, s[18:19]
	s_add_u32 s18, s18, s15
	s_addc_u32 s19, s19, 0
	global_load_dword v90, v70, s[18:19]
	s_add_u32 s18, s18, s15
	s_addc_u32 s19, s19, 0
	global_load_dword v91, v70, s[18:19]
	s_add_u32 s18, s18, s15
	s_addc_u32 s19, s19, 0
	global_load_dword v92, v70, s[18:19]
	s_add_u32 s18, s18, s15
	s_addc_u32 s19, s19, 0
	global_load_dword v93, v70, s[18:19]
	s_add_u32 s18, s18, s15
	s_addc_u32 s19, s19, 0
	global_load_dword v94, v70, s[18:19]
	s_add_u32 s18, s18, s15
	s_addc_u32 s19, s19, 0
	global_load_dword v95, v70, s[18:19]
	s_waitcnt vmcnt(27)
	ds_write_b32 v68, v96
	ds_write_b32 v68, v97 offset:2080
	ds_write_b32 v68, v98 offset:4160
	ds_write_b32 v68, v99 offset:6240
	ds_write_b32 v68, v100 offset:8320
	ds_write_b32 v68, v101 offset:10400
	ds_write_b32 v68, v102 offset:12480
	ds_write_b32 v68, v103 offset:14560
	s_waitcnt lgkmcnt(0)
	s_barrier
	s_lshl_b32 s12, s34, 6
	s_lshr_b32 s13, s34, 1
	s_lshl_b32 s13, s13, 8
	s_and_b32 s15, s34, 1
	s_lshl_b32 s15, s15, 6
	s_add_i32 s13, s13, s15
	s_and_b32 s15, s79, 1
	s_cmp_eq_u32 s79, 1
	s_cselect_b32 s15, 0x80, 0
	s_cmp_eq_u32 s79, 4
	s_cselect_b32 s15, 0x80, s15
	s_add_i32 s13, s13, s15
	s_cmp_eq_u32 s36, 0xb00
	s_cselect_b32 s12, s13, s12
	s_mov_b32 s14, 0x30000
	s_cmp_eq_u32 s79, 1
	s_cselect_b32 s14, 0x30000, s14
	s_cmp_eq_u32 s79, 2
	s_cselect_b32 s14, 0xb30000, s14
	s_cmp_eq_u32 s79, 3
	s_cselect_b32 s14, 0x10b0000, s14
	s_cmp_eq_u32 s79, 4
	s_cselect_b32 s14, 0x10b0000, s14
	s_cmp_eq_u32 s79, 5
	s_cselect_b32 s14, 0x1bb0000, s14
	s_cmp_eq_u32 s79, 6
	s_cselect_b32 s14, 0x2130000, s14
	s_cmp_eq_u32 s79, 7
	s_cselect_b32 s14, 0x28f0000, s14
	s_cmp_eq_u32 s79, 6
	s_cselect_b32 s15, 1, 0
	s_cmp_ge_u32 s34, 24
	s_cselect_b32 s13, s15, 0
	s_cmp_eq_u32 s13, 1
	s_cselect_b32 s14, 0x2430000, s14
	s_cselect_b32 s13, 0x600, 0
	s_sub_i32 s12, s12, s13
	s_mul_i32 s12, s12, s37
	s_lshl_b32 s13, s35, 6
	s_add_i32 s12, s12, s13
	s_lshl_b32 s12, s12, 1
	s_add_u32 s12, s12, s14
	s_add_u32 s20, s30, s12
	s_addc_u32 s21, s31, 0
	v_mul_u32_u24_e32 v71, s37, v66
	v_add_lshl_u32 v71, v71, v67, 1
	ds_read_b32 v104, v69
	ds_read_b32 v105, v69 offset:260
	ds_read_b32 v106, v69 offset:520
	ds_read_b32 v107, v69 offset:780
	ds_read_b32 v108, v69 offset:1040
	ds_read_b32 v109, v69 offset:1300
	ds_read_b32 v110, v69 offset:1560
	ds_read_b32 v111, v69 offset:1820
	s_waitcnt lgkmcnt(0)
	v_cvt_pk_bf16_f32 v116, v104, v105
	v_cvt_pk_bf16_f32 v117, v106, v107
	v_cvt_pk_bf16_f32 v118, v108, v109
	v_cvt_pk_bf16_f32 v119, v110, v111
	global_store_dwordx4 v71, v[116:119], s[20:21]
	s_barrier
	s_add_i32 s4, s2, 0xb00
	s_mov_b32 s79, 0
	s_cmp_ge_u32 s4, 0x2c0
	s_addc_u32 s79, s79, 0
	s_cmp_ge_u32 s4, 0x580
	s_addc_u32 s79, s79, 0
	s_cmp_ge_u32 s4, 0x840
	s_addc_u32 s79, s79, 0
	s_cmp_ge_u32 s4, 0xb00
	s_addc_u32 s79, s79, 0
	s_cmp_ge_u32 s4, 0xdc0
	s_addc_u32 s79, s79, 0
	s_cmp_ge_u32 s4, 0x1080
	s_addc_u32 s79, s79, 0
	s_cmp_ge_u32 s4, 0x13c0
	s_addc_u32 s79, s79, 0
	s_mul_i32 s12, s79, 0x2c0
	s_cmp_eq_u32 s79, 7
	s_cselect_b32 s13, 0x80, 0
	s_add_i32 s12, s12, s13
	s_sub_i32 s6, s4, s12
	s_cmp_eq_u32 s79, 2
	s_cselect_b32 s14, 1, 0
	s_cmp_eq_u32 s79, 5
	s_cselect_b32 s14, 1, s14
	s_mul_i32 s12, s6, 0x5d2
	s_lshr_b32 s12, s12, 16
	s_mul_i32 s15, s12, 44
	s_sub_i32 s15, s6, s15
	s_lshr_b32 s13, s6, 4
	s_and_b32 s35, s6, 15
	s_cmp_eq_u32 s14, 1
	s_cselect_b32 s34, s12, s13
	s_cselect_b32 s35, s15, s35
	s_movk_i32 s37, 0x400
	s_cselect_b32 s37, 0xb00, s37
	s_movk_i32 s36, 0xb00
	s_cselect_b32 s36, 0x400, s36
	s_cmp_eq_u32 s79, 7
	s_cselect_b32 s36, 0x400, s36
	s_cmp_eq_u32 s79, 6
	s_cselect_b32 s36, 0xd00, s36
	s_lshl_b32 s12, s79, 3
	s_lshr_b64 s[12:13], s[22:23], s12
	s_and_b32 s12, s12, 0xff
	s_add_i32 s13, s12, 1
	v_readlane_b32 s16, v241, s12
	v_readlane_b32 s17, v241, s13
	v_mul_u32_u24_e32 v70, s36, v65
	s_mul_i32 s14, s35, s36
	s_add_i32 s14, s14, s34
	s_lshl_b32 s14, s14, 8
	v_add_lshl_u32 v70, v70, v64, 2
	s_add_u32 s18, s16, s14
	s_addc_u32 s19, s17, 0
	s_lshl_b32 s15, s36, 5
	global_load_dword v96, v70, s[18:19]
	s_add_u32 s18, s18, s15
	s_addc_u32 s19, s19, 0
	global_load_dword v97, v70, s[18:19]
	s_add_u32 s18, s18, s15
	s_addc_u32 s19, s19, 0
	global_load_dword v98, v70, s[18:19]
	s_add_u32 s18, s18, s15
	s_addc_u32 s19, s19, 0
	global_load_dword v99, v70, s[18:19]
	s_add_u32 s18, s18, s15
	s_addc_u32 s19, s19, 0
	global_load_dword v100, v70, s[18:19]
	s_add_u32 s18, s18, s15
	s_addc_u32 s19, s19, 0
	global_load_dword v101, v70, s[18:19]
	s_add_u32 s18, s18, s15
	s_addc_u32 s19, s19, 0
	global_load_dword v102, v70, s[18:19]
	s_add_u32 s18, s18, s15
	s_addc_u32 s19, s19, 0
	global_load_dword v103, v70, s[18:19]
	s_waitcnt vmcnt(27)
	ds_write_b32 v68, v72
	ds_write_b32 v68, v73 offset:2080
	ds_write_b32 v68, v74 offset:4160
	ds_write_b32 v68, v75 offset:6240
	ds_write_b32 v68, v76 offset:8320
	ds_write_b32 v68, v77 offset:10400
	ds_write_b32 v68, v78 offset:12480
	ds_write_b32 v68, v79 offset:14560
	s_waitcnt lgkmcnt(0)
	s_barrier
	s_lshl_b32 s12, s65, 6
	s_lshr_b32 s13, s65, 1
	s_lshl_b32 s13, s13, 8
	s_and_b32 s15, s65, 1
	s_lshl_b32 s15, s15, 6
	s_add_i32 s13, s13, s15
	s_and_b32 s15, s64, 1
	s_cmp_eq_u32 s64, 1
	s_cselect_b32 s15, 0x80, 0
	s_cmp_eq_u32 s64, 4
	s_cselect_b32 s15, 0x80, s15
	s_add_i32 s13, s13, s15
	s_cmp_eq_u32 s67, 0xb00
	s_cselect_b32 s12, s13, s12
	s_mov_b32 s14, 0x30000
	s_cmp_eq_u32 s64, 1
	s_cselect_b32 s14, 0x30000, s14
	s_cmp_eq_u32 s64, 2
	s_cselect_b32 s14, 0xb30000, s14
	s_cmp_eq_u32 s64, 3
	s_cselect_b32 s14, 0x10b0000, s14
	s_cmp_eq_u32 s64, 4
	s_cselect_b32 s14, 0x10b0000, s14
	s_cmp_eq_u32 s64, 5
	s_cselect_b32 s14, 0x1bb0000, s14
	s_cmp_eq_u32 s64, 6
	s_cselect_b32 s14, 0x2130000, s14
	s_cmp_eq_u32 s64, 7
	s_cselect_b32 s14, 0x28f0000, s14
	s_cmp_eq_u32 s64, 6
	s_cselect_b32 s15, 1, 0
	s_cmp_ge_u32 s65, 24
	s_cselect_b32 s13, s15, 0
	s_cmp_eq_u32 s13, 1
	s_cselect_b32 s14, 0x2430000, s14
	s_cselect_b32 s13, 0x600, 0
	s_sub_i32 s12, s12, s13
	s_mul_i32 s12, s12, s68
	s_lshl_b32 s13, s66, 6
	s_add_i32 s12, s12, s13
	s_lshl_b32 s12, s12, 1
	s_add_u32 s12, s12, s14
	s_add_u32 s20, s30, s12
	s_addc_u32 s21, s31, 0
	v_mul_u32_u24_e32 v71, s68, v66
	v_add_lshl_u32 v71, v71, v67, 1
	ds_read_b32 v104, v69
	ds_read_b32 v105, v69 offset:260
	ds_read_b32 v106, v69 offset:520
	ds_read_b32 v107, v69 offset:780
	ds_read_b32 v108, v69 offset:1040
	ds_read_b32 v109, v69 offset:1300
	ds_read_b32 v110, v69 offset:1560
	ds_read_b32 v111, v69 offset:1820
	s_waitcnt lgkmcnt(0)
	v_cvt_pk_bf16_f32 v112, v104, v105
	v_cvt_pk_bf16_f32 v113, v106, v107
	v_cvt_pk_bf16_f32 v114, v108, v109
	v_cvt_pk_bf16_f32 v115, v110, v111
	global_store_dwordx4 v71, v[112:115], s[20:21]
	s_barrier
	s_add_i32 s4, s2, 0xc00
	s_mov_b32 s64, 0
	s_cmp_ge_u32 s4, 0x2c0
	s_addc_u32 s64, s64, 0
	s_cmp_ge_u32 s4, 0x580
	s_addc_u32 s64, s64, 0
	s_cmp_ge_u32 s4, 0x840
	s_addc_u32 s64, s64, 0
	s_cmp_ge_u32 s4, 0xb00
	s_addc_u32 s64, s64, 0
	s_cmp_ge_u32 s4, 0xdc0
	s_addc_u32 s64, s64, 0
	s_cmp_ge_u32 s4, 0x1080
	s_addc_u32 s64, s64, 0
	s_cmp_ge_u32 s4, 0x13c0
	s_addc_u32 s64, s64, 0
	s_mul_i32 s12, s64, 0x2c0
	s_cmp_eq_u32 s64, 7
	s_cselect_b32 s13, 0x80, 0
	s_add_i32 s12, s12, s13
	s_sub_i32 s6, s4, s12
	s_cmp_eq_u32 s64, 2
	s_cselect_b32 s14, 1, 0
	s_cmp_eq_u32 s64, 5
	s_cselect_b32 s14, 1, s14
	s_mul_i32 s12, s6, 0x5d2
	s_lshr_b32 s12, s12, 16
	s_mul_i32 s15, s12, 44
	s_sub_i32 s15, s6, s15
	s_lshr_b32 s13, s6, 4
	s_and_b32 s66, s6, 15
	s_cmp_eq_u32 s14, 1
	s_cselect_b32 s65, s12, s13
	s_cselect_b32 s66, s15, s66
	s_movk_i32 s68, 0x400
	s_cselect_b32 s68, 0xb00, s68
	s_movk_i32 s67, 0xb00
	s_cselect_b32 s67, 0x400, s67
	s_cmp_eq_u32 s64, 7
	s_cselect_b32 s67, 0x400, s67
	s_cmp_eq_u32 s64, 6
	s_cselect_b32 s67, 0xd00, s67
	s_lshl_b32 s12, s64, 3
	s_lshr_b64 s[12:13], s[22:23], s12
	s_and_b32 s12, s12, 0xff
	s_add_i32 s13, s12, 1
	v_readlane_b32 s16, v241, s12
	v_readlane_b32 s17, v241, s13
	v_mul_u32_u24_e32 v70, s67, v65
	s_mul_i32 s14, s66, s67
	s_add_i32 s14, s14, s65
	s_lshl_b32 s14, s14, 8
	v_add_lshl_u32 v70, v70, v64, 2
	s_add_u32 s18, s16, s14
	s_addc_u32 s19, s17, 0
	s_lshl_b32 s15, s67, 5
	global_load_dword v72, v70, s[18:19]
	s_add_u32 s18, s18, s15
	s_addc_u32 s19, s19, 0
	global_load_dword v73, v70, s[18:19]
	s_add_u32 s18, s18, s15
	s_addc_u32 s19, s19, 0
	global_load_dword v74, v70, s[18:19]
	s_add_u32 s18, s18, s15
	s_addc_u32 s19, s19, 0
	global_load_dword v75, v70, s[18:19]
	s_add_u32 s18, s18, s15
	s_addc_u32 s19, s19, 0
	global_load_dword v76, v70, s[18:19]
	s_add_u32 s18, s18, s15
	s_addc_u32 s19, s19, 0
	global_load_dword v77, v70, s[18:19]
	s_add_u32 s18, s18, s15
	s_addc_u32 s19, s19, 0
	global_load_dword v78, v70, s[18:19]
	s_add_u32 s18, s18, s15
	s_addc_u32 s19, s19, 0
	global_load_dword v79, v70, s[18:19]
	s_waitcnt vmcnt(27)
	ds_write_b32 v68, v80
	ds_write_b32 v68, v81 offset:2080
	ds_write_b32 v68, v82 offset:4160
	ds_write_b32 v68, v83 offset:6240
	ds_write_b32 v68, v84 offset:8320
	ds_write_b32 v68, v85 offset:10400
	ds_write_b32 v68, v86 offset:12480
	ds_write_b32 v68, v87 offset:14560
	s_waitcnt lgkmcnt(0)
	s_barrier
	s_lshl_b32 s12, s70, 6
	s_lshr_b32 s13, s70, 1
	s_lshl_b32 s13, s13, 8
	s_and_b32 s15, s70, 1
	s_lshl_b32 s15, s15, 6
	s_add_i32 s13, s13, s15
	s_and_b32 s15, s69, 1
	s_cmp_eq_u32 s69, 1
	s_cselect_b32 s15, 0x80, 0
	s_cmp_eq_u32 s69, 4
	s_cselect_b32 s15, 0x80, s15
	s_add_i32 s13, s13, s15
	s_cmp_eq_u32 s72, 0xb00
	s_cselect_b32 s12, s13, s12
	s_mov_b32 s14, 0x30000
	s_cmp_eq_u32 s69, 1
	s_cselect_b32 s14, 0x30000, s14
	s_cmp_eq_u32 s69, 2
	s_cselect_b32 s14, 0xb30000, s14
	s_cmp_eq_u32 s69, 3
	s_cselect_b32 s14, 0x10b0000, s14
	s_cmp_eq_u32 s69, 4
	s_cselect_b32 s14, 0x10b0000, s14
	s_cmp_eq_u32 s69, 5
	s_cselect_b32 s14, 0x1bb0000, s14
	s_cmp_eq_u32 s69, 6
	s_cselect_b32 s14, 0x2130000, s14
	s_cmp_eq_u32 s69, 7
	s_cselect_b32 s14, 0x28f0000, s14
	s_cmp_eq_u32 s69, 6
	s_cselect_b32 s15, 1, 0
	s_cmp_ge_u32 s70, 24
	s_cselect_b32 s13, s15, 0
	s_cmp_eq_u32 s13, 1
	s_cselect_b32 s14, 0x2430000, s14
	s_cselect_b32 s13, 0x600, 0
	s_sub_i32 s12, s12, s13
	s_mul_i32 s12, s12, s73
	s_lshl_b32 s13, s71, 6
	s_add_i32 s12, s12, s13
	s_lshl_b32 s12, s12, 1
	s_add_u32 s12, s12, s14
	s_add_u32 s20, s30, s12
	s_addc_u32 s21, s31, 0
	v_mul_u32_u24_e32 v71, s73, v66
	v_add_lshl_u32 v71, v71, v67, 1
	ds_read_b32 v104, v69
	ds_read_b32 v105, v69 offset:260
	ds_read_b32 v106, v69 offset:520
	ds_read_b32 v107, v69 offset:780
	ds_read_b32 v108, v69 offset:1040
	ds_read_b32 v109, v69 offset:1300
	ds_read_b32 v110, v69 offset:1560
	ds_read_b32 v111, v69 offset:1820
	s_waitcnt lgkmcnt(0)
	v_cvt_pk_bf16_f32 v116, v104, v105
	v_cvt_pk_bf16_f32 v117, v106, v107
	v_cvt_pk_bf16_f32 v118, v108, v109
	v_cvt_pk_bf16_f32 v119, v110, v111
	global_store_dwordx4 v71, v[116:119], s[20:21]
	s_barrier
	s_add_i32 s4, s2, 0xd00
	s_mov_b32 s69, 0
	s_cmp_ge_u32 s4, 0x2c0
	s_addc_u32 s69, s69, 0
	s_cmp_ge_u32 s4, 0x580
	s_addc_u32 s69, s69, 0
	s_cmp_ge_u32 s4, 0x840
	s_addc_u32 s69, s69, 0
	s_cmp_ge_u32 s4, 0xb00
	s_addc_u32 s69, s69, 0
	s_cmp_ge_u32 s4, 0xdc0
	s_addc_u32 s69, s69, 0
	s_cmp_ge_u32 s4, 0x1080
	s_addc_u32 s69, s69, 0
	s_cmp_ge_u32 s4, 0x13c0
	s_addc_u32 s69, s69, 0
	s_mul_i32 s12, s69, 0x2c0
	s_cmp_eq_u32 s69, 7
	s_cselect_b32 s13, 0x80, 0
	s_add_i32 s12, s12, s13
	s_sub_i32 s6, s4, s12
	s_cmp_eq_u32 s69, 2
	s_cselect_b32 s14, 1, 0
	s_cmp_eq_u32 s69, 5
	s_cselect_b32 s14, 1, s14
	s_mul_i32 s12, s6, 0x5d2
	s_lshr_b32 s12, s12, 16
	s_mul_i32 s15, s12, 44
	s_sub_i32 s15, s6, s15
	s_lshr_b32 s13, s6, 4
	s_and_b32 s71, s6, 15
	s_cmp_eq_u32 s14, 1
	s_cselect_b32 s70, s12, s13
	s_cselect_b32 s71, s15, s71
	s_movk_i32 s73, 0x400
	s_cselect_b32 s73, 0xb00, s73
	s_movk_i32 s72, 0xb00
	s_cselect_b32 s72, 0x400, s72
	s_cmp_eq_u32 s69, 7
	s_cselect_b32 s72, 0x400, s72
	s_cmp_eq_u32 s69, 6
	s_cselect_b32 s72, 0xd00, s72
	s_lshl_b32 s12, s69, 3
	s_lshr_b64 s[12:13], s[22:23], s12
	s_and_b32 s12, s12, 0xff
	s_add_i32 s13, s12, 1
	v_readlane_b32 s16, v241, s12
	v_readlane_b32 s17, v241, s13
	v_mul_u32_u24_e32 v70, s72, v65
	s_mul_i32 s14, s71, s72
	s_add_i32 s14, s14, s70
	s_lshl_b32 s14, s14, 8
	v_add_lshl_u32 v70, v70, v64, 2
	s_add_u32 s18, s16, s14
	s_addc_u32 s19, s17, 0
	s_lshl_b32 s15, s72, 5
	global_load_dword v80, v70, s[18:19]
	s_add_u32 s18, s18, s15
	s_addc_u32 s19, s19, 0
	global_load_dword v81, v70, s[18:19]
	s_add_u32 s18, s18, s15
	s_addc_u32 s19, s19, 0
	global_load_dword v82, v70, s[18:19]
	s_add_u32 s18, s18, s15
	s_addc_u32 s19, s19, 0
	global_load_dword v83, v70, s[18:19]
	s_add_u32 s18, s18, s15
	s_addc_u32 s19, s19, 0
	global_load_dword v84, v70, s[18:19]
	s_add_u32 s18, s18, s15
	s_addc_u32 s19, s19, 0
	global_load_dword v85, v70, s[18:19]
	s_add_u32 s18, s18, s15
	s_addc_u32 s19, s19, 0
	global_load_dword v86, v70, s[18:19]
	s_add_u32 s18, s18, s15
	s_addc_u32 s19, s19, 0
	global_load_dword v87, v70, s[18:19]
	s_waitcnt vmcnt(27)
	ds_write_b32 v68, v88
	ds_write_b32 v68, v89 offset:2080
	ds_write_b32 v68, v90 offset:4160
	ds_write_b32 v68, v91 offset:6240
	ds_write_b32 v68, v92 offset:8320
	ds_write_b32 v68, v93 offset:10400
	ds_write_b32 v68, v94 offset:12480
	ds_write_b32 v68, v95 offset:14560
	s_waitcnt lgkmcnt(0)
	s_barrier
	s_lshl_b32 s12, s75, 6
	s_lshr_b32 s13, s75, 1
	s_lshl_b32 s13, s13, 8
	s_and_b32 s15, s75, 1
	s_lshl_b32 s15, s15, 6
	s_add_i32 s13, s13, s15
	s_and_b32 s15, s74, 1
	s_cmp_eq_u32 s74, 1
	s_cselect_b32 s15, 0x80, 0
	s_cmp_eq_u32 s74, 4
	s_cselect_b32 s15, 0x80, s15
	s_add_i32 s13, s13, s15
	s_cmp_eq_u32 s77, 0xb00
	s_cselect_b32 s12, s13, s12
	s_mov_b32 s14, 0x30000
	s_cmp_eq_u32 s74, 1
	s_cselect_b32 s14, 0x30000, s14
	s_cmp_eq_u32 s74, 2
	s_cselect_b32 s14, 0xb30000, s14
	s_cmp_eq_u32 s74, 3
	s_cselect_b32 s14, 0x10b0000, s14
	s_cmp_eq_u32 s74, 4
	s_cselect_b32 s14, 0x10b0000, s14
	s_cmp_eq_u32 s74, 5
	s_cselect_b32 s14, 0x1bb0000, s14
	s_cmp_eq_u32 s74, 6
	s_cselect_b32 s14, 0x2130000, s14
	s_cmp_eq_u32 s74, 7
	s_cselect_b32 s14, 0x28f0000, s14
	s_cmp_eq_u32 s74, 6
	s_cselect_b32 s15, 1, 0
	s_cmp_ge_u32 s75, 24
	s_cselect_b32 s13, s15, 0
	s_cmp_eq_u32 s13, 1
	s_cselect_b32 s14, 0x2430000, s14
	s_cselect_b32 s13, 0x600, 0
	s_sub_i32 s12, s12, s13
	s_mul_i32 s12, s12, s78
	s_lshl_b32 s13, s76, 6
	s_add_i32 s12, s12, s13
	s_lshl_b32 s12, s12, 1
	s_add_u32 s12, s12, s14
	s_add_u32 s20, s30, s12
	s_addc_u32 s21, s31, 0
	v_mul_u32_u24_e32 v71, s78, v66
	v_add_lshl_u32 v71, v71, v67, 1
	ds_read_b32 v104, v69
	ds_read_b32 v105, v69 offset:260
	ds_read_b32 v106, v69 offset:520
	ds_read_b32 v107, v69 offset:780
	ds_read_b32 v108, v69 offset:1040
	ds_read_b32 v109, v69 offset:1300
	ds_read_b32 v110, v69 offset:1560
	ds_read_b32 v111, v69 offset:1820
	s_waitcnt lgkmcnt(0)
	v_cvt_pk_bf16_f32 v112, v104, v105
	v_cvt_pk_bf16_f32 v113, v106, v107
	v_cvt_pk_bf16_f32 v114, v108, v109
	v_cvt_pk_bf16_f32 v115, v110, v111
	global_store_dwordx4 v71, v[112:115], s[20:21]
	s_barrier
	s_add_i32 s4, s2, 0xe00
	s_mov_b32 s74, 0
	s_cmp_ge_u32 s4, 0x2c0
	s_addc_u32 s74, s74, 0
	s_cmp_ge_u32 s4, 0x580
	s_addc_u32 s74, s74, 0
	s_cmp_ge_u32 s4, 0x840
	s_addc_u32 s74, s74, 0
	s_cmp_ge_u32 s4, 0xb00
	s_addc_u32 s74, s74, 0
	s_cmp_ge_u32 s4, 0xdc0
	s_addc_u32 s74, s74, 0
	s_cmp_ge_u32 s4, 0x1080
	s_addc_u32 s74, s74, 0
	s_cmp_ge_u32 s4, 0x13c0
	s_addc_u32 s74, s74, 0
	s_mul_i32 s12, s74, 0x2c0
	s_cmp_eq_u32 s74, 7
	s_cselect_b32 s13, 0x80, 0
	s_add_i32 s12, s12, s13
	s_sub_i32 s6, s4, s12
	s_cmp_eq_u32 s74, 2
	s_cselect_b32 s14, 1, 0
	s_cmp_eq_u32 s74, 5
	s_cselect_b32 s14, 1, s14
	s_mul_i32 s12, s6, 0x5d2
	s_lshr_b32 s12, s12, 16
	s_mul_i32 s15, s12, 44
	s_sub_i32 s15, s6, s15
	s_lshr_b32 s13, s6, 4
	s_and_b32 s76, s6, 15
	s_cmp_eq_u32 s14, 1
	s_cselect_b32 s75, s12, s13
	s_cselect_b32 s76, s15, s76
	s_movk_i32 s78, 0x400
	s_cselect_b32 s78, 0xb00, s78
	s_movk_i32 s77, 0xb00
	s_cselect_b32 s77, 0x400, s77
	s_cmp_eq_u32 s74, 7
	s_cselect_b32 s77, 0x400, s77
	s_cmp_eq_u32 s74, 6
	s_cselect_b32 s77, 0xd00, s77
	s_lshl_b32 s12, s74, 3
	s_lshr_b64 s[12:13], s[22:23], s12
	s_and_b32 s12, s12, 0xff
	s_add_i32 s13, s12, 1
	v_readlane_b32 s16, v241, s12
	v_readlane_b32 s17, v241, s13
	v_mul_u32_u24_e32 v70, s77, v65
	s_mul_i32 s14, s76, s77
	s_add_i32 s14, s14, s75
	s_lshl_b32 s14, s14, 8
	v_add_lshl_u32 v70, v70, v64, 2
	s_add_u32 s18, s16, s14
	s_addc_u32 s19, s17, 0
	s_lshl_b32 s15, s77, 5
	global_load_dword v88, v70, s[18:19]
	s_add_u32 s18, s18, s15
	s_addc_u32 s19, s19, 0
	global_load_dword v89, v70, s[18:19]
	s_add_u32 s18, s18, s15
	s_addc_u32 s19, s19, 0
	global_load_dword v90, v70, s[18:19]
	s_add_u32 s18, s18, s15
	s_addc_u32 s19, s19, 0
	global_load_dword v91, v70, s[18:19]
	s_add_u32 s18, s18, s15
	s_addc_u32 s19, s19, 0
	global_load_dword v92, v70, s[18:19]
	s_add_u32 s18, s18, s15
	s_addc_u32 s19, s19, 0
	global_load_dword v93, v70, s[18:19]
	s_add_u32 s18, s18, s15
	s_addc_u32 s19, s19, 0
	global_load_dword v94, v70, s[18:19]
	s_add_u32 s18, s18, s15
	s_addc_u32 s19, s19, 0
	global_load_dword v95, v70, s[18:19]
	s_waitcnt vmcnt(27)
	ds_write_b32 v68, v96
	ds_write_b32 v68, v97 offset:2080
	ds_write_b32 v68, v98 offset:4160
	ds_write_b32 v68, v99 offset:6240
	ds_write_b32 v68, v100 offset:8320
	ds_write_b32 v68, v101 offset:10400
	ds_write_b32 v68, v102 offset:12480
	ds_write_b32 v68, v103 offset:14560
	s_waitcnt lgkmcnt(0)
	s_barrier
	s_lshl_b32 s12, s34, 6
	s_lshr_b32 s13, s34, 1
	s_lshl_b32 s13, s13, 8
	s_and_b32 s15, s34, 1
	s_lshl_b32 s15, s15, 6
	s_add_i32 s13, s13, s15
	s_and_b32 s15, s79, 1
	s_cmp_eq_u32 s79, 1
	s_cselect_b32 s15, 0x80, 0
	s_cmp_eq_u32 s79, 4
	s_cselect_b32 s15, 0x80, s15
	s_add_i32 s13, s13, s15
	s_cmp_eq_u32 s36, 0xb00
	s_cselect_b32 s12, s13, s12
	s_mov_b32 s14, 0x30000
	s_cmp_eq_u32 s79, 1
	s_cselect_b32 s14, 0x30000, s14
	s_cmp_eq_u32 s79, 2
	s_cselect_b32 s14, 0xb30000, s14
	s_cmp_eq_u32 s79, 3
	s_cselect_b32 s14, 0x10b0000, s14
	s_cmp_eq_u32 s79, 4
	s_cselect_b32 s14, 0x10b0000, s14
	s_cmp_eq_u32 s79, 5
	s_cselect_b32 s14, 0x1bb0000, s14
	s_cmp_eq_u32 s79, 6
	s_cselect_b32 s14, 0x2130000, s14
	s_cmp_eq_u32 s79, 7
	s_cselect_b32 s14, 0x28f0000, s14
	s_cmp_eq_u32 s79, 6
	s_cselect_b32 s15, 1, 0
	s_cmp_ge_u32 s34, 24
	s_cselect_b32 s13, s15, 0
	s_cmp_eq_u32 s13, 1
	s_cselect_b32 s14, 0x2430000, s14
	s_cselect_b32 s13, 0x600, 0
	s_sub_i32 s12, s12, s13
	s_mul_i32 s12, s12, s37
	s_lshl_b32 s13, s35, 6
	s_add_i32 s12, s12, s13
	s_lshl_b32 s12, s12, 1
	s_add_u32 s12, s12, s14
	s_add_u32 s20, s30, s12
	s_addc_u32 s21, s31, 0
	v_mul_u32_u24_e32 v71, s37, v66
	v_add_lshl_u32 v71, v71, v67, 1
	ds_read_b32 v104, v69
	ds_read_b32 v105, v69 offset:260
	ds_read_b32 v106, v69 offset:520
	ds_read_b32 v107, v69 offset:780
	ds_read_b32 v108, v69 offset:1040
	ds_read_b32 v109, v69 offset:1300
	ds_read_b32 v110, v69 offset:1560
	ds_read_b32 v111, v69 offset:1820
	s_waitcnt lgkmcnt(0)
	v_cvt_pk_bf16_f32 v116, v104, v105
	v_cvt_pk_bf16_f32 v117, v106, v107
	v_cvt_pk_bf16_f32 v118, v108, v109
	v_cvt_pk_bf16_f32 v119, v110, v111
	global_store_dwordx4 v71, v[116:119], s[20:21]
	s_barrier
	s_add_i32 s4, s2, 0xf00
	s_mov_b32 s79, 0
	s_cmp_ge_u32 s4, 0x2c0
	s_addc_u32 s79, s79, 0
	s_cmp_ge_u32 s4, 0x580
	s_addc_u32 s79, s79, 0
	s_cmp_ge_u32 s4, 0x840
	s_addc_u32 s79, s79, 0
	s_cmp_ge_u32 s4, 0xb00
	s_addc_u32 s79, s79, 0
	s_cmp_ge_u32 s4, 0xdc0
	s_addc_u32 s79, s79, 0
	s_cmp_ge_u32 s4, 0x1080
	s_addc_u32 s79, s79, 0
	s_cmp_ge_u32 s4, 0x13c0
	s_addc_u32 s79, s79, 0
	s_mul_i32 s12, s79, 0x2c0
	s_cmp_eq_u32 s79, 7
	s_cselect_b32 s13, 0x80, 0
	s_add_i32 s12, s12, s13
	s_sub_i32 s6, s4, s12
	s_cmp_eq_u32 s79, 2
	s_cselect_b32 s14, 1, 0
	s_cmp_eq_u32 s79, 5
	s_cselect_b32 s14, 1, s14
	s_mul_i32 s12, s6, 0x5d2
	s_lshr_b32 s12, s12, 16
	s_mul_i32 s15, s12, 44
	s_sub_i32 s15, s6, s15
	s_lshr_b32 s13, s6, 4
	s_and_b32 s35, s6, 15
	s_cmp_eq_u32 s14, 1
	s_cselect_b32 s34, s12, s13
	s_cselect_b32 s35, s15, s35
	s_movk_i32 s37, 0x400
	s_cselect_b32 s37, 0xb00, s37
	s_movk_i32 s36, 0xb00
	s_cselect_b32 s36, 0x400, s36
	s_cmp_eq_u32 s79, 7
	s_cselect_b32 s36, 0x400, s36
	s_cmp_eq_u32 s79, 6
	s_cselect_b32 s36, 0xd00, s36
	s_lshl_b32 s12, s79, 3
	s_lshr_b64 s[12:13], s[22:23], s12
	s_and_b32 s12, s12, 0xff
	s_add_i32 s13, s12, 1
	v_readlane_b32 s16, v241, s12
	v_readlane_b32 s17, v241, s13
	v_mul_u32_u24_e32 v70, s36, v65
	s_mul_i32 s14, s35, s36
	s_add_i32 s14, s14, s34
	s_lshl_b32 s14, s14, 8
	v_add_lshl_u32 v70, v70, v64, 2
	s_add_u32 s18, s16, s14
	s_addc_u32 s19, s17, 0
	s_lshl_b32 s15, s36, 5
	global_load_dword v96, v70, s[18:19]
	s_add_u32 s18, s18, s15
	s_addc_u32 s19, s19, 0
	global_load_dword v97, v70, s[18:19]
	s_add_u32 s18, s18, s15
	s_addc_u32 s19, s19, 0
	global_load_dword v98, v70, s[18:19]
	s_add_u32 s18, s18, s15
	s_addc_u32 s19, s19, 0
	global_load_dword v99, v70, s[18:19]
	s_add_u32 s18, s18, s15
	s_addc_u32 s19, s19, 0
	global_load_dword v100, v70, s[18:19]
	s_add_u32 s18, s18, s15
	s_addc_u32 s19, s19, 0
	global_load_dword v101, v70, s[18:19]
	s_add_u32 s18, s18, s15
	s_addc_u32 s19, s19, 0
	global_load_dword v102, v70, s[18:19]
	s_add_u32 s18, s18, s15
	s_addc_u32 s19, s19, 0
	global_load_dword v103, v70, s[18:19]
	s_waitcnt vmcnt(27)
	ds_write_b32 v68, v72
	ds_write_b32 v68, v73 offset:2080
	ds_write_b32 v68, v74 offset:4160
	ds_write_b32 v68, v75 offset:6240
	ds_write_b32 v68, v76 offset:8320
	ds_write_b32 v68, v77 offset:10400
	ds_write_b32 v68, v78 offset:12480
	ds_write_b32 v68, v79 offset:14560
	s_waitcnt lgkmcnt(0)
	s_barrier
	s_lshl_b32 s12, s65, 6
	s_lshr_b32 s13, s65, 1
	s_lshl_b32 s13, s13, 8
	s_and_b32 s15, s65, 1
	s_lshl_b32 s15, s15, 6
	s_add_i32 s13, s13, s15
	s_and_b32 s15, s64, 1
	s_cmp_eq_u32 s64, 1
	s_cselect_b32 s15, 0x80, 0
	s_cmp_eq_u32 s64, 4
	s_cselect_b32 s15, 0x80, s15
	s_add_i32 s13, s13, s15
	s_cmp_eq_u32 s67, 0xb00
	s_cselect_b32 s12, s13, s12
	s_mov_b32 s14, 0x30000
	s_cmp_eq_u32 s64, 1
	s_cselect_b32 s14, 0x30000, s14
	s_cmp_eq_u32 s64, 2
	s_cselect_b32 s14, 0xb30000, s14
	s_cmp_eq_u32 s64, 3
	s_cselect_b32 s14, 0x10b0000, s14
	s_cmp_eq_u32 s64, 4
	s_cselect_b32 s14, 0x10b0000, s14
	s_cmp_eq_u32 s64, 5
	s_cselect_b32 s14, 0x1bb0000, s14
	s_cmp_eq_u32 s64, 6
	s_cselect_b32 s14, 0x2130000, s14
	s_cmp_eq_u32 s64, 7
	s_cselect_b32 s14, 0x28f0000, s14
	s_cmp_eq_u32 s64, 6
	s_cselect_b32 s15, 1, 0
	s_cmp_ge_u32 s65, 24
	s_cselect_b32 s13, s15, 0
	s_cmp_eq_u32 s13, 1
	s_cselect_b32 s14, 0x2430000, s14
	s_cselect_b32 s13, 0x600, 0
	s_sub_i32 s12, s12, s13
	s_mul_i32 s12, s12, s68
	s_lshl_b32 s13, s66, 6
	s_add_i32 s12, s12, s13
	s_lshl_b32 s12, s12, 1
	s_add_u32 s12, s12, s14
	s_add_u32 s20, s30, s12
	s_addc_u32 s21, s31, 0
	v_mul_u32_u24_e32 v71, s68, v66
	v_add_lshl_u32 v71, v71, v67, 1
	ds_read_b32 v104, v69
	ds_read_b32 v105, v69 offset:260
	ds_read_b32 v106, v69 offset:520
	ds_read_b32 v107, v69 offset:780
	ds_read_b32 v108, v69 offset:1040
	ds_read_b32 v109, v69 offset:1300
	ds_read_b32 v110, v69 offset:1560
	ds_read_b32 v111, v69 offset:1820
	s_waitcnt lgkmcnt(0)
	v_cvt_pk_bf16_f32 v112, v104, v105
	v_cvt_pk_bf16_f32 v113, v106, v107
	v_cvt_pk_bf16_f32 v114, v108, v109
	v_cvt_pk_bf16_f32 v115, v110, v111
	global_store_dwordx4 v71, v[112:115], s[20:21]
	s_barrier
	s_add_i32 s4, s2, 0x1000
	s_mov_b32 s64, 0
	s_cmp_ge_u32 s4, 0x2c0
	s_addc_u32 s64, s64, 0
	s_cmp_ge_u32 s4, 0x580
	s_addc_u32 s64, s64, 0
	s_cmp_ge_u32 s4, 0x840
	s_addc_u32 s64, s64, 0
	s_cmp_ge_u32 s4, 0xb00
	s_addc_u32 s64, s64, 0
	s_cmp_ge_u32 s4, 0xdc0
	s_addc_u32 s64, s64, 0
	s_cmp_ge_u32 s4, 0x1080
	s_addc_u32 s64, s64, 0
	s_cmp_ge_u32 s4, 0x13c0
	s_addc_u32 s64, s64, 0
	s_mul_i32 s12, s64, 0x2c0
	s_cmp_eq_u32 s64, 7
	s_cselect_b32 s13, 0x80, 0
	s_add_i32 s12, s12, s13
	s_sub_i32 s6, s4, s12
	s_cmp_eq_u32 s64, 2
	s_cselect_b32 s14, 1, 0
	s_cmp_eq_u32 s64, 5
	s_cselect_b32 s14, 1, s14
	s_mul_i32 s12, s6, 0x5d2
	s_lshr_b32 s12, s12, 16
	s_mul_i32 s15, s12, 44
	s_sub_i32 s15, s6, s15
	s_lshr_b32 s13, s6, 4
	s_and_b32 s66, s6, 15
	s_cmp_eq_u32 s14, 1
	s_cselect_b32 s65, s12, s13
	s_cselect_b32 s66, s15, s66
	s_movk_i32 s68, 0x400
	s_cselect_b32 s68, 0xb00, s68
	s_movk_i32 s67, 0xb00
	s_cselect_b32 s67, 0x400, s67
	s_cmp_eq_u32 s64, 7
	s_cselect_b32 s67, 0x400, s67
	s_cmp_eq_u32 s64, 6
	s_cselect_b32 s67, 0xd00, s67
	s_lshl_b32 s12, s64, 3
	s_lshr_b64 s[12:13], s[22:23], s12
	s_and_b32 s12, s12, 0xff
	s_add_i32 s13, s12, 1
	v_readlane_b32 s16, v241, s12
	v_readlane_b32 s17, v241, s13
	v_mul_u32_u24_e32 v70, s67, v65
	s_mul_i32 s14, s66, s67
	s_add_i32 s14, s14, s65
	s_lshl_b32 s14, s14, 8
	v_add_lshl_u32 v70, v70, v64, 2
	s_add_u32 s18, s16, s14
	s_addc_u32 s19, s17, 0
	s_lshl_b32 s15, s67, 5
	global_load_dword v72, v70, s[18:19]
	s_add_u32 s18, s18, s15
	s_addc_u32 s19, s19, 0
	global_load_dword v73, v70, s[18:19]
	s_add_u32 s18, s18, s15
	s_addc_u32 s19, s19, 0
	global_load_dword v74, v70, s[18:19]
	s_add_u32 s18, s18, s15
	s_addc_u32 s19, s19, 0
	global_load_dword v75, v70, s[18:19]
	s_add_u32 s18, s18, s15
	s_addc_u32 s19, s19, 0
	global_load_dword v76, v70, s[18:19]
	s_add_u32 s18, s18, s15
	s_addc_u32 s19, s19, 0
	global_load_dword v77, v70, s[18:19]
	s_add_u32 s18, s18, s15
	s_addc_u32 s19, s19, 0
	global_load_dword v78, v70, s[18:19]
	s_add_u32 s18, s18, s15
	s_addc_u32 s19, s19, 0
	global_load_dword v79, v70, s[18:19]
	s_waitcnt vmcnt(27)
	ds_write_b32 v68, v80
	ds_write_b32 v68, v81 offset:2080
	ds_write_b32 v68, v82 offset:4160
	ds_write_b32 v68, v83 offset:6240
	ds_write_b32 v68, v84 offset:8320
	ds_write_b32 v68, v85 offset:10400
	ds_write_b32 v68, v86 offset:12480
	ds_write_b32 v68, v87 offset:14560
	s_waitcnt lgkmcnt(0)
	s_barrier
	s_lshl_b32 s12, s70, 6
	s_lshr_b32 s13, s70, 1
	s_lshl_b32 s13, s13, 8
	s_and_b32 s15, s70, 1
	s_lshl_b32 s15, s15, 6
	s_add_i32 s13, s13, s15
	s_and_b32 s15, s69, 1
	s_cmp_eq_u32 s69, 1
	s_cselect_b32 s15, 0x80, 0
	s_cmp_eq_u32 s69, 4
	s_cselect_b32 s15, 0x80, s15
	s_add_i32 s13, s13, s15
	s_cmp_eq_u32 s72, 0xb00
	s_cselect_b32 s12, s13, s12
	s_mov_b32 s14, 0x30000
	s_cmp_eq_u32 s69, 1
	s_cselect_b32 s14, 0x30000, s14
	s_cmp_eq_u32 s69, 2
	s_cselect_b32 s14, 0xb30000, s14
	s_cmp_eq_u32 s69, 3
	s_cselect_b32 s14, 0x10b0000, s14
	s_cmp_eq_u32 s69, 4
	s_cselect_b32 s14, 0x10b0000, s14
	s_cmp_eq_u32 s69, 5
	s_cselect_b32 s14, 0x1bb0000, s14
	s_cmp_eq_u32 s69, 6
	s_cselect_b32 s14, 0x2130000, s14
	s_cmp_eq_u32 s69, 7
	s_cselect_b32 s14, 0x28f0000, s14
	s_cmp_eq_u32 s69, 6
	s_cselect_b32 s15, 1, 0
	s_cmp_ge_u32 s70, 24
	s_cselect_b32 s13, s15, 0
	s_cmp_eq_u32 s13, 1
	s_cselect_b32 s14, 0x2430000, s14
	s_cselect_b32 s13, 0x600, 0
	s_sub_i32 s12, s12, s13
	s_mul_i32 s12, s12, s73
	s_lshl_b32 s13, s71, 6
	s_add_i32 s12, s12, s13
	s_lshl_b32 s12, s12, 1
	s_add_u32 s12, s12, s14
	s_add_u32 s20, s30, s12
	s_addc_u32 s21, s31, 0
	v_mul_u32_u24_e32 v71, s73, v66
	v_add_lshl_u32 v71, v71, v67, 1
	ds_read_b32 v104, v69
	ds_read_b32 v105, v69 offset:260
	ds_read_b32 v106, v69 offset:520
	ds_read_b32 v107, v69 offset:780
	ds_read_b32 v108, v69 offset:1040
	ds_read_b32 v109, v69 offset:1300
	ds_read_b32 v110, v69 offset:1560
	ds_read_b32 v111, v69 offset:1820
	s_waitcnt lgkmcnt(0)
	v_cvt_pk_bf16_f32 v116, v104, v105
	v_cvt_pk_bf16_f32 v117, v106, v107
	v_cvt_pk_bf16_f32 v118, v108, v109
	v_cvt_pk_bf16_f32 v119, v110, v111
	global_store_dwordx4 v71, v[116:119], s[20:21]
	s_barrier
	s_add_i32 s4, s2, 0x1100
	s_mov_b32 s69, 0
	s_cmp_ge_u32 s4, 0x2c0
	s_addc_u32 s69, s69, 0
	s_cmp_ge_u32 s4, 0x580
	s_addc_u32 s69, s69, 0
	s_cmp_ge_u32 s4, 0x840
	s_addc_u32 s69, s69, 0
	s_cmp_ge_u32 s4, 0xb00
	s_addc_u32 s69, s69, 0
	s_cmp_ge_u32 s4, 0xdc0
	s_addc_u32 s69, s69, 0
	s_cmp_ge_u32 s4, 0x1080
	s_addc_u32 s69, s69, 0
	s_cmp_ge_u32 s4, 0x13c0
	s_addc_u32 s69, s69, 0
	s_mul_i32 s12, s69, 0x2c0
	s_cmp_eq_u32 s69, 7
	s_cselect_b32 s13, 0x80, 0
	s_add_i32 s12, s12, s13
	s_sub_i32 s6, s4, s12
	s_cmp_eq_u32 s69, 2
	s_cselect_b32 s14, 1, 0
	s_cmp_eq_u32 s69, 5
	s_cselect_b32 s14, 1, s14
	s_mul_i32 s12, s6, 0x5d2
	s_lshr_b32 s12, s12, 16
	s_mul_i32 s15, s12, 44
	s_sub_i32 s15, s6, s15
	s_lshr_b32 s13, s6, 4
	s_and_b32 s71, s6, 15
	s_cmp_eq_u32 s14, 1
	s_cselect_b32 s70, s12, s13
	s_cselect_b32 s71, s15, s71
	s_movk_i32 s73, 0x400
	s_cselect_b32 s73, 0xb00, s73
	s_movk_i32 s72, 0xb00
	s_cselect_b32 s72, 0x400, s72
	s_cmp_eq_u32 s69, 7
	s_cselect_b32 s72, 0x400, s72
	s_cmp_eq_u32 s69, 6
	s_cselect_b32 s72, 0xd00, s72
	s_lshl_b32 s12, s69, 3
	s_lshr_b64 s[12:13], s[22:23], s12
	s_and_b32 s12, s12, 0xff
	s_add_i32 s13, s12, 1
	v_readlane_b32 s16, v241, s12
	v_readlane_b32 s17, v241, s13
	v_mul_u32_u24_e32 v70, s72, v65
	s_mul_i32 s14, s71, s72
	s_add_i32 s14, s14, s70
	s_lshl_b32 s14, s14, 8
	v_add_lshl_u32 v70, v70, v64, 2
	s_add_u32 s18, s16, s14
	s_addc_u32 s19, s17, 0
	s_lshl_b32 s15, s72, 5
	global_load_dword v80, v70, s[18:19]
	s_add_u32 s18, s18, s15
	s_addc_u32 s19, s19, 0
	global_load_dword v81, v70, s[18:19]
	s_add_u32 s18, s18, s15
	s_addc_u32 s19, s19, 0
	global_load_dword v82, v70, s[18:19]
	s_add_u32 s18, s18, s15
	s_addc_u32 s19, s19, 0
	global_load_dword v83, v70, s[18:19]
	s_add_u32 s18, s18, s15
	s_addc_u32 s19, s19, 0
	global_load_dword v84, v70, s[18:19]
	s_add_u32 s18, s18, s15
	s_addc_u32 s19, s19, 0
	global_load_dword v85, v70, s[18:19]
	s_add_u32 s18, s18, s15
	s_addc_u32 s19, s19, 0
	global_load_dword v86, v70, s[18:19]
	s_add_u32 s18, s18, s15
	s_addc_u32 s19, s19, 0
	global_load_dword v87, v70, s[18:19]
	s_waitcnt vmcnt(27)
	ds_write_b32 v68, v88
	ds_write_b32 v68, v89 offset:2080
	ds_write_b32 v68, v90 offset:4160
	ds_write_b32 v68, v91 offset:6240
	ds_write_b32 v68, v92 offset:8320
	ds_write_b32 v68, v93 offset:10400
	ds_write_b32 v68, v94 offset:12480
	ds_write_b32 v68, v95 offset:14560
	s_waitcnt lgkmcnt(0)
	s_barrier
	s_lshl_b32 s12, s75, 6
	s_lshr_b32 s13, s75, 1
	s_lshl_b32 s13, s13, 8
	s_and_b32 s15, s75, 1
	s_lshl_b32 s15, s15, 6
	s_add_i32 s13, s13, s15
	s_and_b32 s15, s74, 1
	s_cmp_eq_u32 s74, 1
	s_cselect_b32 s15, 0x80, 0
	s_cmp_eq_u32 s74, 4
	s_cselect_b32 s15, 0x80, s15
	s_add_i32 s13, s13, s15
	s_cmp_eq_u32 s77, 0xb00
	s_cselect_b32 s12, s13, s12
	s_mov_b32 s14, 0x30000
	s_cmp_eq_u32 s74, 1
	s_cselect_b32 s14, 0x30000, s14
	s_cmp_eq_u32 s74, 2
	s_cselect_b32 s14, 0xb30000, s14
	s_cmp_eq_u32 s74, 3
	s_cselect_b32 s14, 0x10b0000, s14
	s_cmp_eq_u32 s74, 4
	s_cselect_b32 s14, 0x10b0000, s14
	s_cmp_eq_u32 s74, 5
	s_cselect_b32 s14, 0x1bb0000, s14
	s_cmp_eq_u32 s74, 6
	s_cselect_b32 s14, 0x2130000, s14
	s_cmp_eq_u32 s74, 7
	s_cselect_b32 s14, 0x28f0000, s14
	s_cmp_eq_u32 s74, 6
	s_cselect_b32 s15, 1, 0
	s_cmp_ge_u32 s75, 24
	s_cselect_b32 s13, s15, 0
	s_cmp_eq_u32 s13, 1
	s_cselect_b32 s14, 0x2430000, s14
	s_cselect_b32 s13, 0x600, 0
	s_sub_i32 s12, s12, s13
	s_mul_i32 s12, s12, s78
	s_lshl_b32 s13, s76, 6
	s_add_i32 s12, s12, s13
	s_lshl_b32 s12, s12, 1
	s_add_u32 s12, s12, s14
	s_add_u32 s20, s30, s12
	s_addc_u32 s21, s31, 0
	v_mul_u32_u24_e32 v71, s78, v66
	v_add_lshl_u32 v71, v71, v67, 1
	ds_read_b32 v104, v69
	ds_read_b32 v105, v69 offset:260
	ds_read_b32 v106, v69 offset:520
	ds_read_b32 v107, v69 offset:780
	ds_read_b32 v108, v69 offset:1040
	ds_read_b32 v109, v69 offset:1300
	ds_read_b32 v110, v69 offset:1560
	ds_read_b32 v111, v69 offset:1820
	s_waitcnt lgkmcnt(0)
	v_cvt_pk_bf16_f32 v112, v104, v105
	v_cvt_pk_bf16_f32 v113, v106, v107
	v_cvt_pk_bf16_f32 v114, v108, v109
	v_cvt_pk_bf16_f32 v115, v110, v111
	global_store_dwordx4 v71, v[112:115], s[20:21]
	s_barrier
	s_add_i32 s4, s2, 0x1200
	s_mov_b32 s74, 0
	s_cmp_ge_u32 s4, 0x2c0
	s_addc_u32 s74, s74, 0
	s_cmp_ge_u32 s4, 0x580
	s_addc_u32 s74, s74, 0
	s_cmp_ge_u32 s4, 0x840
	s_addc_u32 s74, s74, 0
	s_cmp_ge_u32 s4, 0xb00
	s_addc_u32 s74, s74, 0
	s_cmp_ge_u32 s4, 0xdc0
	s_addc_u32 s74, s74, 0
	s_cmp_ge_u32 s4, 0x1080
	s_addc_u32 s74, s74, 0
	s_cmp_ge_u32 s4, 0x13c0
	s_addc_u32 s74, s74, 0
	s_mul_i32 s12, s74, 0x2c0
	s_cmp_eq_u32 s74, 7
	s_cselect_b32 s13, 0x80, 0
	s_add_i32 s12, s12, s13
	s_sub_i32 s6, s4, s12
	s_cmp_eq_u32 s74, 2
	s_cselect_b32 s14, 1, 0
	s_cmp_eq_u32 s74, 5
	s_cselect_b32 s14, 1, s14
	s_mul_i32 s12, s6, 0x5d2
	s_lshr_b32 s12, s12, 16
	s_mul_i32 s15, s12, 44
	s_sub_i32 s15, s6, s15
	s_lshr_b32 s13, s6, 4
	s_and_b32 s76, s6, 15
	s_cmp_eq_u32 s14, 1
	s_cselect_b32 s75, s12, s13
	s_cselect_b32 s76, s15, s76
	s_movk_i32 s78, 0x400
	s_cselect_b32 s78, 0xb00, s78
	s_movk_i32 s77, 0xb00
	s_cselect_b32 s77, 0x400, s77
	s_cmp_eq_u32 s74, 7
	s_cselect_b32 s77, 0x400, s77
	s_cmp_eq_u32 s74, 6
	s_cselect_b32 s77, 0xd00, s77
	s_lshl_b32 s12, s74, 3
	s_lshr_b64 s[12:13], s[22:23], s12
	s_and_b32 s12, s12, 0xff
	s_add_i32 s13, s12, 1
	v_readlane_b32 s16, v241, s12
	v_readlane_b32 s17, v241, s13
	v_mul_u32_u24_e32 v70, s77, v65
	s_mul_i32 s14, s76, s77
	s_add_i32 s14, s14, s75
	s_lshl_b32 s14, s14, 8
	v_add_lshl_u32 v70, v70, v64, 2
	s_add_u32 s18, s16, s14
	s_addc_u32 s19, s17, 0
	s_lshl_b32 s15, s77, 5
	global_load_dword v88, v70, s[18:19]
	s_add_u32 s18, s18, s15
	s_addc_u32 s19, s19, 0
	global_load_dword v89, v70, s[18:19]
	s_add_u32 s18, s18, s15
	s_addc_u32 s19, s19, 0
	global_load_dword v90, v70, s[18:19]
	s_add_u32 s18, s18, s15
	s_addc_u32 s19, s19, 0
	global_load_dword v91, v70, s[18:19]
	s_add_u32 s18, s18, s15
	s_addc_u32 s19, s19, 0
	global_load_dword v92, v70, s[18:19]
	s_add_u32 s18, s18, s15
	s_addc_u32 s19, s19, 0
	global_load_dword v93, v70, s[18:19]
	s_add_u32 s18, s18, s15
	s_addc_u32 s19, s19, 0
	global_load_dword v94, v70, s[18:19]
	s_add_u32 s18, s18, s15
	s_addc_u32 s19, s19, 0
	global_load_dword v95, v70, s[18:19]
	s_waitcnt vmcnt(27)
	ds_write_b32 v68, v96
	ds_write_b32 v68, v97 offset:2080
	ds_write_b32 v68, v98 offset:4160
	ds_write_b32 v68, v99 offset:6240
	ds_write_b32 v68, v100 offset:8320
	ds_write_b32 v68, v101 offset:10400
	ds_write_b32 v68, v102 offset:12480
	ds_write_b32 v68, v103 offset:14560
	s_waitcnt lgkmcnt(0)
	s_barrier
	s_lshl_b32 s12, s34, 6
	s_lshr_b32 s13, s34, 1
	s_lshl_b32 s13, s13, 8
	s_and_b32 s15, s34, 1
	s_lshl_b32 s15, s15, 6
	s_add_i32 s13, s13, s15
	s_and_b32 s15, s79, 1
	s_cmp_eq_u32 s79, 1
	s_cselect_b32 s15, 0x80, 0
	s_cmp_eq_u32 s79, 4
	s_cselect_b32 s15, 0x80, s15
	s_add_i32 s13, s13, s15
	s_cmp_eq_u32 s36, 0xb00
	s_cselect_b32 s12, s13, s12
	s_mov_b32 s14, 0x30000
	s_cmp_eq_u32 s79, 1
	s_cselect_b32 s14, 0x30000, s14
	s_cmp_eq_u32 s79, 2
	s_cselect_b32 s14, 0xb30000, s14
	s_cmp_eq_u32 s79, 3
	s_cselect_b32 s14, 0x10b0000, s14
	s_cmp_eq_u32 s79, 4
	s_cselect_b32 s14, 0x10b0000, s14
	s_cmp_eq_u32 s79, 5
	s_cselect_b32 s14, 0x1bb0000, s14
	s_cmp_eq_u32 s79, 6
	s_cselect_b32 s14, 0x2130000, s14
	s_cmp_eq_u32 s79, 7
	s_cselect_b32 s14, 0x28f0000, s14
	s_cmp_eq_u32 s79, 6
	s_cselect_b32 s15, 1, 0
	s_cmp_ge_u32 s34, 24
	s_cselect_b32 s13, s15, 0
	s_cmp_eq_u32 s13, 1
	s_cselect_b32 s14, 0x2430000, s14
	s_cselect_b32 s13, 0x600, 0
	s_sub_i32 s12, s12, s13
	s_mul_i32 s12, s12, s37
	s_lshl_b32 s13, s35, 6
	s_add_i32 s12, s12, s13
	s_lshl_b32 s12, s12, 1
	s_add_u32 s12, s12, s14
	s_add_u32 s20, s30, s12
	s_addc_u32 s21, s31, 0
	v_mul_u32_u24_e32 v71, s37, v66
	v_add_lshl_u32 v71, v71, v67, 1
	ds_read_b32 v104, v69
	ds_read_b32 v105, v69 offset:260
	ds_read_b32 v106, v69 offset:520
	ds_read_b32 v107, v69 offset:780
	ds_read_b32 v108, v69 offset:1040
	ds_read_b32 v109, v69 offset:1300
	ds_read_b32 v110, v69 offset:1560
	ds_read_b32 v111, v69 offset:1820
	s_waitcnt lgkmcnt(0)
	v_cvt_pk_bf16_f32 v116, v104, v105
	v_cvt_pk_bf16_f32 v117, v106, v107
	v_cvt_pk_bf16_f32 v118, v108, v109
	v_cvt_pk_bf16_f32 v119, v110, v111
	global_store_dwordx4 v71, v[116:119], s[20:21]
	s_barrier
	s_add_i32 s4, s2, 0x1300
	s_mov_b32 s79, 0
	s_cmp_ge_u32 s4, 0x2c0
	s_addc_u32 s79, s79, 0
	s_cmp_ge_u32 s4, 0x580
	s_addc_u32 s79, s79, 0
	s_cmp_ge_u32 s4, 0x840
	s_addc_u32 s79, s79, 0
	s_cmp_ge_u32 s4, 0xb00
	s_addc_u32 s79, s79, 0
	s_cmp_ge_u32 s4, 0xdc0
	s_addc_u32 s79, s79, 0
	s_cmp_ge_u32 s4, 0x1080
	s_addc_u32 s79, s79, 0
	s_cmp_ge_u32 s4, 0x13c0
	s_addc_u32 s79, s79, 0
	s_mul_i32 s12, s79, 0x2c0
	s_cmp_eq_u32 s79, 7
	s_cselect_b32 s13, 0x80, 0
	s_add_i32 s12, s12, s13
	s_sub_i32 s6, s4, s12
	s_cmp_eq_u32 s79, 2
	s_cselect_b32 s14, 1, 0
	s_cmp_eq_u32 s79, 5
	s_cselect_b32 s14, 1, s14
	s_mul_i32 s12, s6, 0x5d2
	s_lshr_b32 s12, s12, 16
	s_mul_i32 s15, s12, 44
	s_sub_i32 s15, s6, s15
	s_lshr_b32 s13, s6, 4
	s_and_b32 s35, s6, 15
	s_cmp_eq_u32 s14, 1
	s_cselect_b32 s34, s12, s13
	s_cselect_b32 s35, s15, s35
	s_movk_i32 s37, 0x400
	s_cselect_b32 s37, 0xb00, s37
	s_movk_i32 s36, 0xb00
	s_cselect_b32 s36, 0x400, s36
	s_cmp_eq_u32 s79, 7
	s_cselect_b32 s36, 0x400, s36
	s_cmp_eq_u32 s79, 6
	s_cselect_b32 s36, 0xd00, s36
	s_lshl_b32 s12, s79, 3
	s_lshr_b64 s[12:13], s[22:23], s12
	s_and_b32 s12, s12, 0xff
	s_add_i32 s13, s12, 1
	v_readlane_b32 s16, v241, s12
	v_readlane_b32 s17, v241, s13
	v_mul_u32_u24_e32 v70, s36, v65
	s_mul_i32 s14, s35, s36
	s_add_i32 s14, s14, s34
	s_lshl_b32 s14, s14, 8
	v_add_lshl_u32 v70, v70, v64, 2
	s_add_u32 s18, s16, s14
	s_addc_u32 s19, s17, 0
	s_lshl_b32 s15, s36, 5
	global_load_dword v96, v70, s[18:19]
	s_add_u32 s18, s18, s15
	s_addc_u32 s19, s19, 0
	global_load_dword v97, v70, s[18:19]
	s_add_u32 s18, s18, s15
	s_addc_u32 s19, s19, 0
	global_load_dword v98, v70, s[18:19]
	s_add_u32 s18, s18, s15
	s_addc_u32 s19, s19, 0
	global_load_dword v99, v70, s[18:19]
	s_add_u32 s18, s18, s15
	s_addc_u32 s19, s19, 0
	global_load_dword v100, v70, s[18:19]
	s_add_u32 s18, s18, s15
	s_addc_u32 s19, s19, 0
	global_load_dword v101, v70, s[18:19]
	s_add_u32 s18, s18, s15
	s_addc_u32 s19, s19, 0
	global_load_dword v102, v70, s[18:19]
	s_add_u32 s18, s18, s15
	s_addc_u32 s19, s19, 0
	global_load_dword v103, v70, s[18:19]
	s_waitcnt vmcnt(27)
	ds_write_b32 v68, v72
	ds_write_b32 v68, v73 offset:2080
	ds_write_b32 v68, v74 offset:4160
	ds_write_b32 v68, v75 offset:6240
	ds_write_b32 v68, v76 offset:8320
	ds_write_b32 v68, v77 offset:10400
	ds_write_b32 v68, v78 offset:12480
	ds_write_b32 v68, v79 offset:14560
	s_waitcnt lgkmcnt(0)
	s_barrier
	s_lshl_b32 s12, s65, 6
	s_lshr_b32 s13, s65, 1
	s_lshl_b32 s13, s13, 8
	s_and_b32 s15, s65, 1
	s_lshl_b32 s15, s15, 6
	s_add_i32 s13, s13, s15
	s_and_b32 s15, s64, 1
	s_cmp_eq_u32 s64, 1
	s_cselect_b32 s15, 0x80, 0
	s_cmp_eq_u32 s64, 4
	s_cselect_b32 s15, 0x80, s15
	s_add_i32 s13, s13, s15
	s_cmp_eq_u32 s67, 0xb00
	s_cselect_b32 s12, s13, s12
	s_mov_b32 s14, 0x30000
	s_cmp_eq_u32 s64, 1
	s_cselect_b32 s14, 0x30000, s14
	s_cmp_eq_u32 s64, 2
	s_cselect_b32 s14, 0xb30000, s14
	s_cmp_eq_u32 s64, 3
	s_cselect_b32 s14, 0x10b0000, s14
	s_cmp_eq_u32 s64, 4
	s_cselect_b32 s14, 0x10b0000, s14
	s_cmp_eq_u32 s64, 5
	s_cselect_b32 s14, 0x1bb0000, s14
	s_cmp_eq_u32 s64, 6
	s_cselect_b32 s14, 0x2130000, s14
	s_cmp_eq_u32 s64, 7
	s_cselect_b32 s14, 0x28f0000, s14
	s_cmp_eq_u32 s64, 6
	s_cselect_b32 s15, 1, 0
	s_cmp_ge_u32 s65, 24
	s_cselect_b32 s13, s15, 0
	s_cmp_eq_u32 s13, 1
	s_cselect_b32 s14, 0x2430000, s14
	s_cselect_b32 s13, 0x600, 0
	s_sub_i32 s12, s12, s13
	s_mul_i32 s12, s12, s68
	s_lshl_b32 s13, s66, 6
	s_add_i32 s12, s12, s13
	s_lshl_b32 s12, s12, 1
	s_add_u32 s12, s12, s14
	s_add_u32 s20, s30, s12
	s_addc_u32 s21, s31, 0
	v_mul_u32_u24_e32 v71, s68, v66
	v_add_lshl_u32 v71, v71, v67, 1
	ds_read_b32 v104, v69
	ds_read_b32 v105, v69 offset:260
	ds_read_b32 v106, v69 offset:520
	ds_read_b32 v107, v69 offset:780
	ds_read_b32 v108, v69 offset:1040
	ds_read_b32 v109, v69 offset:1300
	ds_read_b32 v110, v69 offset:1560
	ds_read_b32 v111, v69 offset:1820
	s_waitcnt lgkmcnt(0)
	v_cvt_pk_bf16_f32 v112, v104, v105
	v_cvt_pk_bf16_f32 v113, v106, v107
	v_cvt_pk_bf16_f32 v114, v108, v109
	v_cvt_pk_bf16_f32 v115, v110, v111
	global_store_dwordx4 v71, v[112:115], s[20:21]
	s_barrier
	s_cmpk_gt_u32 s2, 0xbf
	s_cselect_b32 s12, 0, 0x1400
	s_add_i32 s4, s2, s12
	s_mov_b32 s64, 0
	s_cmp_ge_u32 s4, 0x2c0
	s_addc_u32 s64, s64, 0
	s_cmp_ge_u32 s4, 0x580
	s_addc_u32 s64, s64, 0
	s_cmp_ge_u32 s4, 0x840
	s_addc_u32 s64, s64, 0
	s_cmp_ge_u32 s4, 0xb00
	s_addc_u32 s64, s64, 0
	s_cmp_ge_u32 s4, 0xdc0
	s_addc_u32 s64, s64, 0
	s_cmp_ge_u32 s4, 0x1080
	s_addc_u32 s64, s64, 0
	s_cmp_ge_u32 s4, 0x13c0
	s_addc_u32 s64, s64, 0
	s_mul_i32 s12, s64, 0x2c0
	s_cmp_eq_u32 s64, 7
	s_cselect_b32 s13, 0x80, 0
	s_add_i32 s12, s12, s13
	s_sub_i32 s6, s4, s12
	s_cmp_eq_u32 s64, 2
	s_cselect_b32 s14, 1, 0
	s_cmp_eq_u32 s64, 5
	s_cselect_b32 s14, 1, s14
	s_mul_i32 s12, s6, 0x5d2
	s_lshr_b32 s12, s12, 16
	s_mul_i32 s15, s12, 44
	s_sub_i32 s15, s6, s15
	s_lshr_b32 s13, s6, 4
	s_and_b32 s66, s6, 15
	s_cmp_eq_u32 s14, 1
	s_cselect_b32 s65, s12, s13
	s_cselect_b32 s66, s15, s66
	s_movk_i32 s68, 0x400
	s_cselect_b32 s68, 0xb00, s68
	s_movk_i32 s67, 0xb00
	s_cselect_b32 s67, 0x400, s67
	s_cmp_eq_u32 s64, 7
	s_cselect_b32 s67, 0x400, s67
	s_cmp_eq_u32 s64, 6
	s_cselect_b32 s67, 0xd00, s67
	s_lshl_b32 s12, s64, 3
	s_lshr_b64 s[12:13], s[22:23], s12
	s_and_b32 s12, s12, 0xff
	s_add_i32 s13, s12, 1
	v_readlane_b32 s16, v241, s12
	v_readlane_b32 s17, v241, s13
	v_mul_u32_u24_e32 v70, s67, v65
	s_mul_i32 s14, s66, s67
	s_add_i32 s14, s14, s65
	s_lshl_b32 s14, s14, 8
	v_add_lshl_u32 v70, v70, v64, 2
	s_add_u32 s18, s16, s14
	s_addc_u32 s19, s17, 0
	s_lshl_b32 s15, s67, 5
	global_load_dword v72, v70, s[18:19]
	s_add_u32 s18, s18, s15
	s_addc_u32 s19, s19, 0
	global_load_dword v73, v70, s[18:19]
	s_add_u32 s18, s18, s15
	s_addc_u32 s19, s19, 0
	global_load_dword v74, v70, s[18:19]
	s_add_u32 s18, s18, s15
	s_addc_u32 s19, s19, 0
	global_load_dword v75, v70, s[18:19]
	s_add_u32 s18, s18, s15
	s_addc_u32 s19, s19, 0
	global_load_dword v76, v70, s[18:19]
	s_add_u32 s18, s18, s15
	s_addc_u32 s19, s19, 0
	global_load_dword v77, v70, s[18:19]
	s_add_u32 s18, s18, s15
	s_addc_u32 s19, s19, 0
	global_load_dword v78, v70, s[18:19]
	s_add_u32 s18, s18, s15
	s_addc_u32 s19, s19, 0
	global_load_dword v79, v70, s[18:19]
	s_waitcnt vmcnt(27)
	ds_write_b32 v68, v80
	ds_write_b32 v68, v81 offset:2080
	ds_write_b32 v68, v82 offset:4160
	ds_write_b32 v68, v83 offset:6240
	ds_write_b32 v68, v84 offset:8320
	ds_write_b32 v68, v85 offset:10400
	ds_write_b32 v68, v86 offset:12480
	ds_write_b32 v68, v87 offset:14560
	s_waitcnt lgkmcnt(0)
	s_barrier
	s_lshl_b32 s12, s70, 6
	s_lshr_b32 s13, s70, 1
	s_lshl_b32 s13, s13, 8
	s_and_b32 s15, s70, 1
	s_lshl_b32 s15, s15, 6
	s_add_i32 s13, s13, s15
	s_and_b32 s15, s69, 1
	s_cmp_eq_u32 s69, 1
	s_cselect_b32 s15, 0x80, 0
	s_cmp_eq_u32 s69, 4
	s_cselect_b32 s15, 0x80, s15
	s_add_i32 s13, s13, s15
	s_cmp_eq_u32 s72, 0xb00
	s_cselect_b32 s12, s13, s12
	s_mov_b32 s14, 0x30000
	s_cmp_eq_u32 s69, 1
	s_cselect_b32 s14, 0x30000, s14
	s_cmp_eq_u32 s69, 2
	s_cselect_b32 s14, 0xb30000, s14
	s_cmp_eq_u32 s69, 3
	s_cselect_b32 s14, 0x10b0000, s14
	s_cmp_eq_u32 s69, 4
	s_cselect_b32 s14, 0x10b0000, s14
	s_cmp_eq_u32 s69, 5
	s_cselect_b32 s14, 0x1bb0000, s14
	s_cmp_eq_u32 s69, 6
	s_cselect_b32 s14, 0x2130000, s14
	s_cmp_eq_u32 s69, 7
	s_cselect_b32 s14, 0x28f0000, s14
	s_cmp_eq_u32 s69, 6
	s_cselect_b32 s15, 1, 0
	s_cmp_ge_u32 s70, 24
	s_cselect_b32 s13, s15, 0
	s_cmp_eq_u32 s13, 1
	s_cselect_b32 s14, 0x2430000, s14
	s_cselect_b32 s13, 0x600, 0
	s_sub_i32 s12, s12, s13
	s_mul_i32 s12, s12, s73
	s_lshl_b32 s13, s71, 6
	s_add_i32 s12, s12, s13
	s_lshl_b32 s12, s12, 1
	s_add_u32 s12, s12, s14
	s_add_u32 s20, s30, s12
	s_addc_u32 s21, s31, 0
	v_mul_u32_u24_e32 v71, s73, v66
	v_add_lshl_u32 v71, v71, v67, 1
	ds_read_b32 v104, v69
	ds_read_b32 v105, v69 offset:260
	ds_read_b32 v106, v69 offset:520
	ds_read_b32 v107, v69 offset:780
	ds_read_b32 v108, v69 offset:1040
	ds_read_b32 v109, v69 offset:1300
	ds_read_b32 v110, v69 offset:1560
	ds_read_b32 v111, v69 offset:1820
	s_waitcnt lgkmcnt(0)
	v_cvt_pk_bf16_f32 v116, v104, v105
	v_cvt_pk_bf16_f32 v117, v106, v107
	v_cvt_pk_bf16_f32 v118, v108, v109
	v_cvt_pk_bf16_f32 v119, v110, v111
	global_store_dwordx4 v71, v[116:119], s[20:21]
	s_barrier
	s_waitcnt vmcnt(19)
	ds_write_b32 v68, v88
	ds_write_b32 v68, v89 offset:2080
	ds_write_b32 v68, v90 offset:4160
	ds_write_b32 v68, v91 offset:6240
	ds_write_b32 v68, v92 offset:8320
	ds_write_b32 v68, v93 offset:10400
	ds_write_b32 v68, v94 offset:12480
	ds_write_b32 v68, v95 offset:14560
	s_waitcnt lgkmcnt(0)
	s_barrier
	s_lshl_b32 s12, s75, 6
	s_lshr_b32 s13, s75, 1
	s_lshl_b32 s13, s13, 8
	s_and_b32 s15, s75, 1
	s_lshl_b32 s15, s15, 6
	s_add_i32 s13, s13, s15
	s_and_b32 s15, s74, 1
	s_cmp_eq_u32 s74, 1
	s_cselect_b32 s15, 0x80, 0
	s_cmp_eq_u32 s74, 4
	s_cselect_b32 s15, 0x80, s15
	s_add_i32 s13, s13, s15
	s_cmp_eq_u32 s77, 0xb00
	s_cselect_b32 s12, s13, s12
	s_mov_b32 s14, 0x30000
	s_cmp_eq_u32 s74, 1
	s_cselect_b32 s14, 0x30000, s14
	s_cmp_eq_u32 s74, 2
	s_cselect_b32 s14, 0xb30000, s14
	s_cmp_eq_u32 s74, 3
	s_cselect_b32 s14, 0x10b0000, s14
	s_cmp_eq_u32 s74, 4
	s_cselect_b32 s14, 0x10b0000, s14
	s_cmp_eq_u32 s74, 5
	s_cselect_b32 s14, 0x1bb0000, s14
	s_cmp_eq_u32 s74, 6
	s_cselect_b32 s14, 0x2130000, s14
	s_cmp_eq_u32 s74, 7
	s_cselect_b32 s14, 0x28f0000, s14
	s_cmp_eq_u32 s74, 6
	s_cselect_b32 s15, 1, 0
	s_cmp_ge_u32 s75, 24
	s_cselect_b32 s13, s15, 0
	s_cmp_eq_u32 s13, 1
	s_cselect_b32 s14, 0x2430000, s14
	s_cselect_b32 s13, 0x600, 0
	s_sub_i32 s12, s12, s13
	s_mul_i32 s12, s12, s78
	s_lshl_b32 s13, s76, 6
	s_add_i32 s12, s12, s13
	s_lshl_b32 s12, s12, 1
	s_add_u32 s12, s12, s14
	s_add_u32 s20, s30, s12
	s_addc_u32 s21, s31, 0
	v_mul_u32_u24_e32 v71, s78, v66
	v_add_lshl_u32 v71, v71, v67, 1
	ds_read_b32 v104, v69
	ds_read_b32 v105, v69 offset:260
	ds_read_b32 v106, v69 offset:520
	ds_read_b32 v107, v69 offset:780
	ds_read_b32 v108, v69 offset:1040
	ds_read_b32 v109, v69 offset:1300
	ds_read_b32 v110, v69 offset:1560
	ds_read_b32 v111, v69 offset:1820
	s_waitcnt lgkmcnt(0)
	v_cvt_pk_bf16_f32 v112, v104, v105
	v_cvt_pk_bf16_f32 v113, v106, v107
	v_cvt_pk_bf16_f32 v114, v108, v109
	v_cvt_pk_bf16_f32 v115, v110, v111
	global_store_dwordx4 v71, v[112:115], s[20:21]
	s_barrier
	s_waitcnt vmcnt(11)
	ds_write_b32 v68, v96
	ds_write_b32 v68, v97 offset:2080
	ds_write_b32 v68, v98 offset:4160
	ds_write_b32 v68, v99 offset:6240
	ds_write_b32 v68, v100 offset:8320
	ds_write_b32 v68, v101 offset:10400
	ds_write_b32 v68, v102 offset:12480
	ds_write_b32 v68, v103 offset:14560
	s_waitcnt lgkmcnt(0)
	s_barrier
	s_lshl_b32 s12, s34, 6
	s_lshr_b32 s13, s34, 1
	s_lshl_b32 s13, s13, 8
	s_and_b32 s15, s34, 1
	s_lshl_b32 s15, s15, 6
	s_add_i32 s13, s13, s15
	s_and_b32 s15, s79, 1
	s_cmp_eq_u32 s79, 1
	s_cselect_b32 s15, 0x80, 0
	s_cmp_eq_u32 s79, 4
	s_cselect_b32 s15, 0x80, s15
	s_add_i32 s13, s13, s15
	s_cmp_eq_u32 s36, 0xb00
	s_cselect_b32 s12, s13, s12
	s_mov_b32 s14, 0x30000
	s_cmp_eq_u32 s79, 1
	s_cselect_b32 s14, 0x30000, s14
	s_cmp_eq_u32 s79, 2
	s_cselect_b32 s14, 0xb30000, s14
	s_cmp_eq_u32 s79, 3
	s_cselect_b32 s14, 0x10b0000, s14
	s_cmp_eq_u32 s79, 4
	s_cselect_b32 s14, 0x10b0000, s14
	s_cmp_eq_u32 s79, 5
	s_cselect_b32 s14, 0x1bb0000, s14
	s_cmp_eq_u32 s79, 6
	s_cselect_b32 s14, 0x2130000, s14
	s_cmp_eq_u32 s79, 7
	s_cselect_b32 s14, 0x28f0000, s14
	s_cmp_eq_u32 s79, 6
	s_cselect_b32 s15, 1, 0
	s_cmp_ge_u32 s34, 24
	s_cselect_b32 s13, s15, 0
	s_cmp_eq_u32 s13, 1
	s_cselect_b32 s14, 0x2430000, s14
	s_cselect_b32 s13, 0x600, 0
	s_sub_i32 s12, s12, s13
	s_mul_i32 s12, s12, s37
	s_lshl_b32 s13, s35, 6
	s_add_i32 s12, s12, s13
	s_lshl_b32 s12, s12, 1
	s_add_u32 s12, s12, s14
	s_add_u32 s20, s30, s12
	s_addc_u32 s21, s31, 0
	v_mul_u32_u24_e32 v71, s37, v66
	v_add_lshl_u32 v71, v71, v67, 1
	ds_read_b32 v104, v69
	ds_read_b32 v105, v69 offset:260
	ds_read_b32 v106, v69 offset:520
	ds_read_b32 v107, v69 offset:780
	ds_read_b32 v108, v69 offset:1040
	ds_read_b32 v109, v69 offset:1300
	ds_read_b32 v110, v69 offset:1560
	ds_read_b32 v111, v69 offset:1820
	s_waitcnt lgkmcnt(0)
	v_cvt_pk_bf16_f32 v116, v104, v105
	v_cvt_pk_bf16_f32 v117, v106, v107
	v_cvt_pk_bf16_f32 v118, v108, v109
	v_cvt_pk_bf16_f32 v119, v110, v111
	global_store_dwordx4 v71, v[116:119], s[20:21]
	s_barrier
	s_cmpk_gt_u32 s2, 0xbf
	s_cbranch_scc1 .Lp0tr_done
	s_waitcnt vmcnt(3)
	ds_write_b32 v68, v72
	ds_write_b32 v68, v73 offset:2080
	ds_write_b32 v68, v74 offset:4160
	ds_write_b32 v68, v75 offset:6240
	ds_write_b32 v68, v76 offset:8320
	ds_write_b32 v68, v77 offset:10400
	ds_write_b32 v68, v78 offset:12480
	ds_write_b32 v68, v79 offset:14560
	s_waitcnt lgkmcnt(0)
	s_barrier
	s_lshl_b32 s12, s65, 6
	s_lshr_b32 s13, s65, 1
	s_lshl_b32 s13, s13, 8
	s_and_b32 s15, s65, 1
	s_lshl_b32 s15, s15, 6
	s_add_i32 s13, s13, s15
	s_and_b32 s15, s64, 1
	s_cmp_eq_u32 s64, 1
	s_cselect_b32 s15, 0x80, 0
	s_cmp_eq_u32 s64, 4
	s_cselect_b32 s15, 0x80, s15
	s_add_i32 s13, s13, s15
	s_cmp_eq_u32 s67, 0xb00
	s_cselect_b32 s12, s13, s12
	s_mov_b32 s14, 0x30000
	s_cmp_eq_u32 s64, 1
	s_cselect_b32 s14, 0x30000, s14
	s_cmp_eq_u32 s64, 2
	s_cselect_b32 s14, 0xb30000, s14
	s_cmp_eq_u32 s64, 3
	s_cselect_b32 s14, 0x10b0000, s14
	s_cmp_eq_u32 s64, 4
	s_cselect_b32 s14, 0x10b0000, s14
	s_cmp_eq_u32 s64, 5
	s_cselect_b32 s14, 0x1bb0000, s14
	s_cmp_eq_u32 s64, 6
	s_cselect_b32 s14, 0x2130000, s14
	s_cmp_eq_u32 s64, 7
	s_cselect_b32 s14, 0x28f0000, s14
	s_cmp_eq_u32 s64, 6
	s_cselect_b32 s15, 1, 0
	s_cmp_ge_u32 s65, 24
	s_cselect_b32 s13, s15, 0
	s_cmp_eq_u32 s13, 1
	s_cselect_b32 s14, 0x2430000, s14
	s_cselect_b32 s13, 0x600, 0
	s_sub_i32 s12, s12, s13
	s_mul_i32 s12, s12, s68
	s_lshl_b32 s13, s66, 6
	s_add_i32 s12, s12, s13
	s_lshl_b32 s12, s12, 1
	s_add_u32 s12, s12, s14
	s_add_u32 s20, s30, s12
	s_addc_u32 s21, s31, 0
	v_mul_u32_u24_e32 v71, s68, v66
	v_add_lshl_u32 v71, v71, v67, 1
	ds_read_b32 v104, v69
	ds_read_b32 v105, v69 offset:260
	ds_read_b32 v106, v69 offset:520
	ds_read_b32 v107, v69 offset:780
	ds_read_b32 v108, v69 offset:1040
	ds_read_b32 v109, v69 offset:1300
	ds_read_b32 v110, v69 offset:1560
	ds_read_b32 v111, v69 offset:1820
	s_waitcnt lgkmcnt(0)
	v_cvt_pk_bf16_f32 v112, v104, v105
	v_cvt_pk_bf16_f32 v113, v106, v107
	v_cvt_pk_bf16_f32 v114, v108, v109
	v_cvt_pk_bf16_f32 v115, v110, v111
	global_store_dwordx4 v71, v[112:115], s[20:21]
	s_barrier
